# speedup vs baseline: 1.0035x; 1.0007x over previous
; DEV int lv(int x) { asm volatile("" : "+v"(x)); return x; }
; DEV int v_st(int k, int c) { const int kk = (k & ~0xC) | ((k & 4) << 1) | ((k & 8) >> 1); return ((kk >> 3) * 4 + (c >> 5)) * 512 + ((kk & 7) * 32 + (c & 31)) * 2; }
; DEV int v_rd_base(int lane) { return ((lane & 3) << 3) | (((lane >> 2) & 3) << 6) | (((lane >> 4) & 1) << 5) | (((lane >> 5) & 1) << 8); }
; #define SWRITE(b) do { *reinterpret_cast<bf16x8*>(V_lds + (b) * 16384 + vst0) = sv0; *reinterpret_cast<bf16x8*>(V_lds + (b) * 16384 + vst1) = sv1; \
;     *reinterpret_cast<bf16x8*>(K_lds + (b) * 16384 + kst0) = sk0; if (SB) *reinterpret_cast<bf16x8*>(K_lds + (b) * 16384 + kst1) = sk1; } while (0)
; template <bool SB>
; DEV void attn_pass(const bf16_t* __restrict__ proj, int qcol, int kcol, int vcol, int q0, f32x16 (&o)[4], float& l_out, unsigned char* lds) {
;     ...
;   const int tid = lv(threadIdx.x), wid = tid >> 6, lane = tid & 63, r32 = lane & 31, hi = lane >> 5;
;   unsigned char* V_lds = lds; unsigned char* K_lds = lds + 32768;
;   float* wsf = (float*)(lds + 65536) + wid * 64; float* al_l = wsf + 32;
;   int* flags = (int*)(lds + 65536 + 2048);
;   bf16x8 qr[NDK];
;   { const bf16_t* Qw = proj + (size_t)(q0 + wid * 32 + r32) * INW + qcol + hi * 8;
; #pragma unroll
;     for (int d0 = 0; d0 < NDK; ++d0) qr[d0] = *reinterpret_cast<const bf16x8*>(Qw + d0 * 16); }
;   const int c0 = q0 >> 6, jhi = c0 + 3, jw = c0 + (wid >> 1);
;   const int sr = tid >> 4, sc = (tid & 15) * 8, vst0 = v_st(sr, sc), vst1 = v_st(32 + sr, sc);
;   const int kr = SB ? sr : (tid >> 3), kc = SB ? sc : (tid & 7) * 8;
;   const int kst0 = kr * KROWB + ((kc * 2) ^ ((kr & 7) << 4)), kst1 = (32 + kr) * KROWB + ((kc * 2) ^ ((kr & 7) << 4));
;   const int vb0 = (int)(uintptr_t)V_lds + v_rd_base(lane);
;   bf16x8 sv0, sv1, sk0, sk1;
;     ...
;   float m_reg = -1e30f, l_reg = 0.f, cum = 1.f;
; #pragma unroll
;   for (int d = 0; d < 4; ++d) o[d] = f32x16{};
;   SLOAD(jhi); SWRITE(0); __syncthreads();
.LBB0_351:
	s_and_b64 s[4:5], s[0:1], exec
	v_readlane_b32 s4, v255, 43
	v_readlane_b32 s5, v255, 44
	s_cselect_b32 s81, s5, s4
	s_lshl_b32 s75, s81, 2
	v_mov_b32_e32 v66, v210
	s_or_b32 s78, s75, 3
	s_ashr_i32 s79, s78, 31
	v_ashrrev_i32_e32 v144, 4, v66
	v_lshlrev_b32_e32 v8, 3, v66
	v_and_b32_e32 v0, 0x78, v8
	s_lshl_b64 s[4:5], s[78:79], 6
	v_ashrrev_i32_e32 v145, 31, v144
	v_lshlrev_b32_e32 v192, 1, v0
	v_lshl_add_u64 v[0:1], s[4:5], 0, v[144:145]
	v_mov_b64_e32 v[2:3], s[86:87]
	v_mad_u64_u32 v[4:5], s[6:7], v0, s85, v[2:3]
	v_lshl_add_u64 v[146:147], v[144:145], 0, 32
	v_readlane_b32 s6, v255, 46
	v_lshl_add_u64 v[6:7], v[146:147], 0, s[4:5]
	v_mad_i32_i24 v5, v1, s85, v5
	s_lshl_b32 s76, s6, 1
	v_mad_u64_u32 v[2:3], s[4:5], v6, s85, v[2:3]
	v_lshl_add_u64 v[0:1], v[4:5], 0, s[76:77]
	v_mad_i32_i24 v3, v7, s85, v3
	v_readlane_b32 s4, v255, 53
	v_lshl_add_u64 v[0:1], v[0:1], 0, v[192:193]
	v_lshl_add_u64 v[6:7], v[2:3], 0, s[76:77]
	s_lshl_b32 s82, s4, 1
	s_mov_b32 s83, s77
	v_lshl_add_u64 v[6:7], v[6:7], 0, v[192:193]
	global_load_dwordx4 v[96:99], v[0:1], off
	global_load_dwordx4 v[100:103], v[6:7], off
	v_lshl_add_u64 v[0:1], v[4:5], 0, s[82:83]
	v_lshl_add_u64 v[2:3], v[2:3], 0, s[82:83]
	v_lshl_add_u64 v[0:1], v[0:1], 0, v[192:193]
	v_lshl_add_u64 v[2:3], v[2:3], 0, v[192:193]
	v_readlane_b32 s4, v255, 55
	s_lshl_b32 s74, s81, 8
	v_ashrrev_i32_e32 v70, 6, v66
	v_and_b32_e32 v68, 31, v66
	global_load_dwordx4 v[104:107], v[0:1], off offset:2048
	global_load_dwordx4 v[108:111], v[2:3], off offset:2048
	v_readlane_b32 s5, v255, 56
	v_lshlrev_b32_e32 v69, 5, v70
	v_or_b32_e32 v3, s74, v68
	v_mov_b64_e32 v[0:1], s[4:5]
	v_bfe_u32 v67, v66, 5, 1
	v_add_u32_e32 v3, v3, v69
	v_mov_b32_e32 v65, v193
	v_lshlrev_b32_e32 v64, 4, v67
	v_mad_i64_i32 v[0:1], s[4:5], v3, s85, v[0:1]
	v_lshl_add_u64 v[0:1], v[0:1], 0, v[64:65]
	global_load_dwordx4 v[112:115], v[0:1], off
	global_load_dwordx4 v[116:119], v[0:1], off offset:32
	global_load_dwordx4 v[120:123], v[0:1], off offset:64
	global_load_dwordx4 v[124:127], v[0:1], off offset:96
	global_load_dwordx4 v[128:131], v[0:1], off offset:128
	global_load_dwordx4 v[132:135], v[0:1], off offset:160
	global_load_dwordx4 v[136:139], v[0:1], off offset:192
	global_load_dwordx4 v[140:143], v[0:1], off offset:224
	v_and_b32_e32 v4, 0xfffff0, v144
	v_lshlrev_b32_e32 v5, 1, v144
	v_lshrrev_b32_e32 v6, 1, v144
	v_bfe_u32 v7, v8, 5, 2
	v_and_b32_e32 v8, 3, v144
	v_add_u32_e32 v9, 32, v144
	v_and_or_b32 v4, v5, 8, v4
	v_and_or_b32 v5, v6, 4, v8
	v_and_b32_e32 v6, 0xfffff0, v9
	v_lshlrev_b32_e32 v8, 1, v9
	v_and_b32_e32 v2, 0x70, v66
	v_lshlrev_b32_e32 v10, 8, v144
	v_lshlrev_b32_e32 v9, 8, v9
	v_lshrrev_b32_e32 v3, 1, v4
	v_and_or_b32 v6, v8, 8, v6
	v_bitop3_b32 v188, v192, v9, v2 bitop3:0xde
	v_bitop3_b32 v189, v192, v10, v2 bitop3:0xde
	v_or_b32_e32 v2, v3, v7
	v_lshrrev_b32_e32 v3, 1, v6
	v_or_b32_e32 v1, v3, v7
	v_lshlrev_b32_e32 v4, 6, v5
	v_and_b32_e32 v5, 48, v192
	v_lshlrev_b32_e32 v0, 9, v2
	v_lshlrev_b32_e32 v1, 9, v1
	v_or3_b32 v190, v0, v4, v5
	v_or3_b32 v191, v1, v4, v5
	v_add_u32_e32 v6, 0, v189
	v_add_u32_e32 v8, 0, v188
	v_add_u32_e32 v0, 0, v190
	v_add_u32_e32 v1, 0, v191
	v_mov_b32_e32 v31, 0
	s_cmp_lt_i32 s81, 0
	v_mov_b32_e32 v30, v31
	v_mov_b32_e32 v29, v31
	v_mov_b32_e32 v28, v31
	v_mov_b32_e32 v27, v31
	v_mov_b32_e32 v26, v31
	v_mov_b32_e32 v25, v31
	v_mov_b32_e32 v24, v31
	s_waitcnt vmcnt(11)
	ds_write_b128 v0, v[96:99]
	s_waitcnt vmcnt(10)
	ds_write_b128 v1, v[100:103]
	s_waitcnt vmcnt(9)
	ds_write_b128 v6, v[104:107] offset:32768
	s_waitcnt vmcnt(8)
	ds_write_b128 v8, v[108:111] offset:32768
	v_mov_b32_e32 v23, v31
	v_mov_b32_e32 v22, v31
	v_mov_b32_e32 v21, v31
	v_mov_b32_e32 v20, v31
	v_mov_b32_e32 v19, v31
	v_mov_b32_e32 v18, v31
	v_mov_b32_e32 v17, v31
	v_mov_b32_e32 v16, v31
	v_mov_b32_e32 v63, v31
	v_mov_b32_e32 v62, v31
	v_mov_b32_e32 v61, v31
	v_mov_b32_e32 v60, v31
	v_mov_b32_e32 v59, v31
	v_mov_b32_e32 v58, v31
	v_mov_b32_e32 v57, v31
	v_mov_b32_e32 v56, v31
	v_mov_b32_e32 v55, v31
	v_mov_b32_e32 v54, v31
	v_mov_b32_e32 v53, v31
	v_mov_b32_e32 v52, v31
	v_mov_b32_e32 v51, v31
	v_mov_b32_e32 v50, v31
	v_mov_b32_e32 v49, v31
	v_mov_b32_e32 v48, v31
	v_mov_b32_e32 v47, v31
	v_mov_b32_e32 v46, v31
	v_mov_b32_e32 v45, v31
	v_mov_b32_e32 v44, v31
	v_mov_b32_e32 v43, v31
	v_mov_b32_e32 v42, v31
	v_mov_b32_e32 v41, v31
	v_mov_b32_e32 v40, v31
	v_mov_b32_e32 v39, v31
	v_mov_b32_e32 v38, v31
	v_mov_b32_e32 v37, v31
	v_mov_b32_e32 v36, v31
	v_mov_b32_e32 v35, v31
	v_mov_b32_e32 v34, v31
	v_mov_b32_e32 v33, v31
	v_mov_b32_e32 v32, v31
	v_mov_b32_e32 v15, v31
	v_mov_b32_e32 v14, v31
	v_mov_b32_e32 v13, v31
	v_mov_b32_e32 v12, v31
	v_mov_b32_e32 v11, v31
	v_mov_b32_e32 v10, v31
	v_mov_b32_e32 v9, v31
	v_mov_b32_e32 v8, v31
	v_mov_b32_e32 v7, v31
	v_mov_b32_e32 v6, v31
	v_mov_b32_e32 v5, v31
	v_mov_b32_e32 v4, v31
	v_mov_b32_e32 v3, v31
	v_mov_b32_e32 v2, v31
	v_mov_b32_e32 v1, v31
	v_mov_b32_e32 v0, v31
	s_waitcnt lgkmcnt(0)
	s_barrier
	s_cbranch_scc1 .LBB0_366
; template <bool SB>
; DEV void attn_pass(const bf16_t* __restrict__ proj, int qcol, int kcol, int vcol, int q0, f32x16 (&o)[4], float& l_out, unsigned char* lds) {
;     ...
;       for (int d0 = 0; d0 < NDK; ++d0) { const int cb = ((d0 * 16 + hi * 8) * 2) ^ ((r32 & 7) << 4);
;         bf16x8 b0 = *reinterpret_cast<const bf16x8*>(Ks + r32 * KROWB + cb);
;         bf16x8 b1 = *reinterpret_cast<const bf16x8*>(Ks + (32 + r32) * KROWB + cb);
;         p0 = __builtin_amdgcn_mfma_f32_32x32x16_bf16(b0, qr[d0], p0, 0, 0, 0);
;         p1 = __builtin_amdgcn_mfma_f32_32x32x16_bf16(b1, qr[d0], p1, 0, 0, 0); }
;       bf16x8 pa0, pa1, pa2, pa3;
;       if constexpr (SB) {
;         const bool diag = (j == jw); const int rl = 32 * (wid & 1) + r32;
;         float T[8], Pg[8];
;     ...
;     if constexpr (SB) { if (lane == 0) flags[buf * 8 + wid] = wdone ? 1 : 0; }
;     __syncthreads();
;     if constexpr (SB) {
;       int all = 1;
; #pragma unroll
;       for (int w = 0; w < 8; ++w) all &= flags[buf * 8 + w];
;       if (all) break;
;     }
	v_and_b32_e32 v0, 63, v66
	v_readlane_b32 s4, v255, 9
	v_lshlrev_b32_e32 v8, 2, v67
	v_lshlrev_b32_e32 v2, 1, v0
	v_lshl_add_u32 v209, v70, 2, s4
	v_lshlrev_b32_e32 v3, 4, v0
	v_lshlrev_b32_e32 v4, 3, v0
	v_and_or_b32 v7, v69, 32, v68
	v_cmp_gt_u32_e64 s[4:5], 32, v0
	v_cmp_eq_u32_e64 s[6:7], 0, v0
	v_or_b32_e32 v0, 1, v8
	v_cmp_lt_u32_e64 s[10:11], v0, v7
	v_or_b32_e32 v0, 2, v8
	v_cmp_lt_u32_e64 s[12:13], v0, v7
	v_or_b32_e32 v0, 3, v8
	v_cmp_lt_u32_e64 s[14:15], v0, v7
	v_or_b32_e32 v0, 9, v8
	v_cmp_lt_u32_e64 s[18:19], v0, v7
	v_or_b32_e32 v0, 10, v8
	v_cmp_lt_u32_e64 s[20:21], v0, v7
	v_or_b32_e32 v0, 11, v8
	v_cmp_lt_u32_e64 s[22:23], v0, v7
	v_or_b32_e32 v0, 17, v8
	v_cmp_lt_u32_e64 s[26:27], v0, v7
	v_or_b32_e32 v0, 18, v8
	v_cmp_lt_u32_e64 s[28:29], v0, v7
	v_or_b32_e32 v0, 19, v8
	v_cmp_lt_u32_e64 s[30:31], v0, v7
	v_or_b32_e32 v0, 25, v8
	v_cmp_lt_u32_e64 s[36:37], v0, v7
	v_or_b32_e32 v0, 26, v8
	v_cmp_lt_u32_e64 s[38:39], v0, v7
	v_or_b32_e32 v0, 27, v8
	v_cmp_lt_u32_e64 s[40:41], v0, v7
	v_or_b32_e32 v0, 33, v8
	v_cmp_lt_u32_e64 s[44:45], v0, v7
	v_or_b32_e32 v0, 34, v8
	v_cmp_lt_u32_e64 s[46:47], v0, v7
	v_or_b32_e32 v0, 35, v8
	v_cmp_lt_u32_e64 s[48:49], v0, v7
	v_or_b32_e32 v0, 41, v8
	v_cmp_lt_u32_e64 s[52:53], v0, v7
	v_or_b32_e32 v0, 42, v8
	v_cmp_lt_u32_e64 s[54:55], v0, v7
	v_or_b32_e32 v0, 43, v8
	v_cmp_lt_u32_e64 s[56:57], v0, v7
	v_or_b32_e32 v0, 49, v8
	v_cmp_lt_u32_e64 s[60:61], v0, v7
	v_or_b32_e32 v0, 50, v8
	v_lshlrev_b32_e32 v5, 4, v66
	s_movk_i32 s8, 0x70
	v_cmp_lt_u32_e64 s[62:63], v0, v7
	v_or_b32_e32 v0, 51, v8
	v_and_b32_e32 v6, 0x70, v5
	v_bitop3_b32 v224, v64, v5, s8 bitop3:0x78
	s_movk_i32 s8, 0x60
	v_cmp_lt_u32_e64 s[64:65], v0, v7
	v_or_b32_e32 v0, 57, v8
	v_bitop3_b32 v227, v64, v6, s8 bitop3:0x36
	s_movk_i32 s8, 0x80
	v_cmp_lt_u32_e64 s[68:69], v0, v7
	v_or_b32_e32 v0, 58, v8
	v_and_b32_e32 v2, 32, v2
	v_bitop3_b32 v228, v64, v6, s8 bitop3:0x36
	s_movk_i32 s8, 0xa0
	v_cmp_lt_u32_e64 s[70:71], v0, v7
	v_or_b32_e32 v0, 59, v8
	s_movk_i32 s83, 0x118
	s_cmp_lg_u32 0, -1
	v_and_b32_e32 v3, 0xc0, v3
	v_bitop3_b32 v229, v64, v6, s8 bitop3:0x36
	s_movk_i32 s8, 0xc0
	v_cmp_lt_u32_e64 s[72:73], v0, v7
	v_and_or_b32 v0, v4, s83, v2
	s_cselect_b32 s83, 0, 0
	v_ashrrev_i32_e32 v1, 7, v66
	v_or_b32_e32 v9, 8, v8
	v_or_b32_e32 v10, 16, v8
	v_or_b32_e32 v11, 24, v8
	v_or_b32_e32 v12, 32, v8
	v_or_b32_e32 v13, 40, v8
	v_or_b32_e32 v14, 48, v8
	v_or_b32_e32 v15, 56, v8
	v_bitop3_b32 v230, v64, v6, s8 bitop3:0x36
	s_movk_i32 s8, 0xe0
	v_add3_u32 v232, v3, s83, v0
	v_mov_b32_e32 v0, 0
	v_add_u32_e32 v208, s75, v1
	v_lshl_add_u32 v223, v68, 8, 0
	s_mov_b32 s79, 0
	v_bitop3_b32 v225, v64, v6, 32 bitop3:0x36
	v_bitop3_b32 v226, v64, v6, 64 bitop3:0x36
	v_bitop3_b32 v231, v64, v6, s8 bitop3:0x36
	v_cmp_lt_u32_e64 s[8:9], v8, v7
	v_cmp_lt_u32_e64 s[16:17], v9, v7
	v_cmp_lt_u32_e64 s[24:25], v10, v7
	v_cmp_lt_u32_e64 s[34:35], v11, v7
	v_cmp_lt_u32_e64 s[42:43], v12, v7
	v_cmp_lt_u32_e64 s[50:51], v13, v7
	v_cmp_lt_u32_e64 s[58:59], v14, v7
	v_cmp_lt_u32_e64 s[66:67], v15, v7
	v_sub_u32_e32 v233, 3, v1
	v_mov_b32_e32 v234, 1.0
	s_mov_b32 s84, s78
	v_mov_b32_e32 v1, v0
	v_mov_b32_e32 v2, v0
	v_mov_b32_e32 v3, v0
	v_mov_b32_e32 v4, v0
	v_mov_b32_e32 v5, v0
	v_mov_b32_e32 v6, v0
	v_mov_b32_e32 v7, v0
	v_mov_b32_e32 v8, v0
	v_mov_b32_e32 v9, v0
	v_mov_b32_e32 v10, v0
	v_mov_b32_e32 v11, v0
	v_mov_b32_e32 v12, v0
	v_mov_b32_e32 v13, v0
	v_mov_b32_e32 v14, v0
	v_mov_b32_e32 v15, v0
	v_mov_b32_e32 v32, v0
	v_mov_b32_e32 v33, v0
	v_mov_b32_e32 v34, v0
	v_mov_b32_e32 v35, v0
	v_mov_b32_e32 v36, v0
	v_mov_b32_e32 v37, v0
	v_mov_b32_e32 v38, v0
	v_mov_b32_e32 v39, v0
	v_mov_b32_e32 v40, v0
	v_mov_b32_e32 v41, v0
	v_mov_b32_e32 v42, v0
	v_mov_b32_e32 v43, v0
	v_mov_b32_e32 v44, v0
	v_mov_b32_e32 v45, v0
	v_mov_b32_e32 v46, v0
	v_mov_b32_e32 v47, v0
	v_mov_b32_e32 v48, v0
	v_mov_b32_e32 v49, v0
	v_mov_b32_e32 v50, v0
	v_mov_b32_e32 v51, v0
	v_mov_b32_e32 v52, v0
	v_mov_b32_e32 v53, v0
	v_mov_b32_e32 v54, v0
	v_mov_b32_e32 v55, v0
	v_mov_b32_e32 v56, v0
	v_mov_b32_e32 v57, v0
	v_mov_b32_e32 v58, v0
	v_mov_b32_e32 v59, v0
	v_mov_b32_e32 v60, v0
	v_mov_b32_e32 v61, v0
	v_mov_b32_e32 v62, v0
	v_mov_b32_e32 v63, v0
	v_mov_b32_e32 v16, v0
	v_mov_b32_e32 v17, v0
	v_mov_b32_e32 v18, v0
	v_mov_b32_e32 v19, v0
	v_mov_b32_e32 v20, v0
	v_mov_b32_e32 v21, v0
	v_mov_b32_e32 v22, v0
	v_mov_b32_e32 v23, v0
	v_mov_b32_e32 v24, v0
	v_mov_b32_e32 v25, v0
	v_mov_b32_e32 v26, v0
	v_mov_b32_e32 v27, v0
	v_mov_b32_e32 v28, v0
	v_mov_b32_e32 v29, v0
	v_mov_b32_e32 v30, v0
	v_mov_b32_e32 v31, v0
	s_waitcnt vmcnt(0)
	v_readfirstlane_b32 s90, v210
	s_nop 3
	s_cmp_lt_u32 s90, 0x100
	s_cbranch_scc1 .Lprio_sb
	s_setprio 1
.Lprio_sb:
	s_branch .LBB0_354
.LBB0_353:
	s_or_b64 exec, exec, s[92:93]
	s_add_i32 s83, s83, 0
	s_add_i32 s83, s83, 0x10800
	v_mov_b32_e32 v68, s83
	s_waitcnt lgkmcnt(0)
	s_barrier
	ds_read_b128 v[64:67], v68
	ds_read_b128 v[68:71], v68 offset:16
	s_add_i32 s79, s79, 1
	s_cmp_lg_u32 s84, 0
	s_cselect_b64 s[88:89], -1, 0
	s_waitcnt lgkmcnt(1)
	v_and_b32_e32 v64, v64, v65
	v_and_b32_e32 v64, v64, v66
	v_and_b32_e32 v64, v64, v67
	s_waitcnt lgkmcnt(0)
	v_and_b32_e32 v64, v64, v68
	v_and_b32_e32 v64, v64, v69
	v_and_b32_e32 v64, v64, v70
	v_and_b32_e32 v64, v64, v71
	v_and_b32_e32 v64, 1, v64
	v_cmp_eq_u32_e32 vcc, 0, v64
	s_and_b64 s[88:89], s[88:89], vcc
	s_add_i32 s84, s84, -1
	s_and_b64 vcc, exec, s[88:89]
	s_cbranch_vccz .LBB0_366

; DEV bf16_t f2bf(float f) { unsigned u = __float_as_uint(f); u += 0x7fffu + ((u >> 16) & 1u); return (bf16_t)(u >> 16); }
; DEV int crow(int r, int hi) { return (r & 3) + 8 * (r >> 2) + 4 * hi; }
; template <bool SPREAD>
; DEV void attn_store(f32x16 (&o)[4], const float* __restrict__ gain, float oscale, bf16_t* __restrict__ mix, int q0, int colbase) {
;     ...
;   unsigned char* sc = shm_raw + wid * 8704;
;   float gn[4];
; #pragma unroll
;   for (int d = 0; d < 4; ++d) gn[d] = gain[d * 32 + r32] * oscale;
; #pragma unroll
;   for (int r = 0; r < 16; ++r) {
;     float ss = o[0][r] * o[0][r] + o[1][r] * o[1][r] + o[2][r] * o[2][r] + o[3][r] * o[3][r];
;     ss += __shfl_xor(ss, 1); ss += __shfl_xor(ss, 2); ss += __shfl_xor(ss, 4); ss += __shfl_xor(ss, 8); ss += __shfl_xor(ss, 16);
;     const float rn = rsqrtf(ss * (1.f / 128.f) + EPS);
;     const int cr = crow(r, hi);
; #pragma unroll
;     for (int d = 0; d < 4; ++d) *reinterpret_cast<bf16_t*>(sc + cr * 272 + (d * 32 + r32) * 2) = f2bf(o[d][r] * rn * gn[d]);
.LBB0_366:
	s_setprio 0
	v_mov_b32_e32 v66, v210
	s_xor_b64 s[8:9], s[0:1], -1
	s_barrier
	s_movk_i32 s0, 0x2200
	v_ashrrev_i32_e32 v67, 6, v66
	v_and_b32_e32 v64, 31, v66
	v_mul_lo_u32 v65, v67, s0
	v_readlane_b32 s0, v255, 59
	v_lshlrev_b32_e32 v68, 2, v64
	v_readlane_b32 s1, v255, 60
	s_nop 4
	global_load_dword v72, v68, s[0:1]
	global_load_dword v71, v68, s[0:1] offset:128
	global_load_dword v70, v68, s[0:1] offset:256
	global_load_dword v69, v68, s[0:1] offset:384
	v_add_u32_e32 v68, 0, v65
	v_lshrrev_b32_e32 v65, 3, v66
	v_and_b32_e32 v73, 4, v65
	v_lshlrev_b32_e32 v76, 1, v64
	v_mul_u32_u24_e32 v73, 0x110, v73
	v_mov_b32_e32 v64, v32
	v_mov_b32_e32 v65, v48
	v_add3_u32 v73, v68, v76, v73
	v_mov_b32_e32 v76, v33
	v_mov_b32_e32 v77, v49
	v_pk_mul_f32 v[64:65], v[64:65], v[64:65]
	v_mov_b32_e32 v74, v16
	v_mov_b32_e32 v75, v0
	v_pk_mul_f32 v[76:77], v[76:77], v[76:77]
	v_mov_b32_e32 v78, v17
	v_mov_b32_e32 v79, v1
	v_pk_mul_f32 v[74:75], v[74:75], v[74:75]
	v_pk_mul_f32 v[78:79], v[78:79], v[78:79]
	v_mov_b32_e32 v80, v76
	v_mov_b32_e32 v81, v64
	v_mov_b32_e32 v64, v77
	v_pk_add_f32 v[64:65], v[80:81], v[64:65]
	v_mov_b32_e32 v76, v79
	v_mov_b32_e32 v77, v75
	v_pk_add_f32 v[64:65], v[76:77], v[64:65]
	v_mov_b32_e32 v79, v74
	v_pk_add_f32 v[64:65], v[78:79], v[64:65]
	ds_bpermute_b32 v75, v221, v65
	ds_bpermute_b32 v74, v221, v64
	s_mov_b32 s0, 0x358637bd
	s_brev_b32 s4, 60
	s_add_i32 s16, 0, 0x18000
	s_add_i32 s15, 0, 0x10000
	s_waitcnt lgkmcnt(0)
	v_pk_add_f32 v[64:65], v[64:65], v[74:75]
	ds_bpermute_b32 v75, v220, v65
	ds_bpermute_b32 v74, v220, v64
	s_add_i32 s14, s75, 4
	s_waitcnt lgkmcnt(0)
	v_pk_add_f32 v[64:65], v[64:65], v[74:75]
	ds_bpermute_b32 v75, v219, v65
	ds_bpermute_b32 v74, v219, v64
	s_waitcnt lgkmcnt(0)
	v_pk_add_f32 v[64:65], v[64:65], v[74:75]
	ds_bpermute_b32 v75, v218, v65
	ds_bpermute_b32 v74, v218, v64
	s_waitcnt lgkmcnt(0)
	v_pk_add_f32 v[64:65], v[64:65], v[74:75]
	ds_bpermute_b32 v75, v217, v65
	ds_bpermute_b32 v74, v217, v64
	s_waitcnt lgkmcnt(0)
	v_pk_add_f32 v[74:75], v[64:65], v[74:75]
	v_mov_b64_e32 v[64:65], s[0:1]
	v_pk_fma_f32 v[74:75], v[74:75], s[4:5], v[64:65] op_sel_hi:[1,0,0]
	s_nop 0
	v_mul_f32_e32 v76, 0x4b800000, v75
	v_cmp_gt_f32_e64 s[0:1], s33, v75
	v_cmp_gt_f32_e32 vcc, s33, v74
	s_nop 0
	v_cndmask_b32_e64 v75, v75, v76, s[0:1]
	v_rsq_f32_e32 v75, v75
	s_nop 0
	v_mul_f32_e32 v76, 0x45800000, v75
	v_cndmask_b32_e64 v75, v75, v76, s[0:1]
	v_mul_f32_e32 v48, v48, v75
	s_waitcnt vmcnt(3)
	v_mul_f32_e32 v48, v72, v48
	v_bfe_u32 v76, v48, 16, 1
	v_mul_f32_e32 v32, v32, v75
	v_add3_u32 v48, v48, v76, s2
	s_waitcnt vmcnt(2)
	v_mul_f32_e32 v32, v71, v32
	ds_write_b16_d16_hi v73, v48
	v_bfe_u32 v48, v32, 16, 1
	v_mul_f32_e32 v0, v0, v75
	v_add3_u32 v32, v32, v48, s2
	s_waitcnt vmcnt(1)
	v_mul_f32_e32 v0, v70, v0
	ds_write_b16_d16_hi v73, v32 offset:64
	v_bfe_u32 v32, v0, 16, 1
	v_add3_u32 v0, v0, v32, s2
	ds_write_b16_d16_hi v73, v0 offset:128
	v_mul_f32_e32 v0, v16, v75
	s_waitcnt vmcnt(0)
	v_mul_f32_e32 v0, v69, v0
	v_bfe_u32 v16, v0, 16, 1
	v_add3_u32 v0, v0, v16, s2
	ds_write_b16_d16_hi v73, v0 offset:192
	v_mul_f32_e32 v0, 0x4b800000, v74
	v_cndmask_b32_e32 v0, v74, v0, vcc
	v_rsq_f32_e32 v0, v0
	v_mov_b32_e32 v48, v19
	v_mul_f32_e32 v16, 0x45800000, v0
	v_cndmask_b32_e32 v0, v0, v16, vcc
	v_mul_f32_e32 v16, v49, v0
	v_mul_f32_e32 v16, v72, v16
	v_bfe_u32 v32, v16, 16, 1
	v_add3_u32 v16, v16, v32, s2
	ds_write_b16_d16_hi v73, v16 offset:272
	v_mul_f32_e32 v16, v33, v0
	v_mul_f32_e32 v16, v71, v16
	v_bfe_u32 v32, v16, 16, 1
	v_mul_f32_e32 v1, v1, v0
	v_add3_u32 v16, v16, v32, s2
	v_mul_f32_e32 v1, v70, v1
	ds_write_b16_d16_hi v73, v16 offset:336
	v_bfe_u32 v16, v1, 16, 1
	v_mul_f32_e32 v0, v17, v0
	v_add3_u32 v1, v1, v16, s2
	v_mul_f32_e32 v0, v69, v0
	ds_write_b16_d16_hi v73, v1 offset:400
	v_bfe_u32 v1, v0, 16, 1
	v_add3_u32 v0, v0, v1, s2
	ds_write_b16_d16_hi v73, v0 offset:464
	v_mov_b32_e32 v0, v34
	v_mov_b32_e32 v1, v50
	v_mov_b32_e32 v32, v35
	v_mov_b32_e32 v33, v51
	v_pk_mul_f32 v[0:1], v[0:1], v[0:1]
	v_mov_b32_e32 v16, v18
	v_mov_b32_e32 v17, v2
	v_pk_mul_f32 v[32:33], v[32:33], v[32:33]
	v_mov_b32_e32 v49, v3
	v_pk_mul_f32 v[16:17], v[16:17], v[16:17]
	v_pk_mul_f32 v[48:49], v[48:49], v[48:49]
	v_mov_b32_e32 v74, v32
	v_mov_b32_e32 v75, v0
	v_mov_b32_e32 v0, v33
	v_pk_add_f32 v[0:1], v[74:75], v[0:1]
	v_mov_b32_e32 v32, v49
	v_mov_b32_e32 v33, v17
	v_pk_add_f32 v[0:1], v[32:33], v[0:1]
	v_mov_b32_e32 v49, v16
	v_pk_add_f32 v[0:1], v[48:49], v[0:1]
	ds_bpermute_b32 v17, v221, v1
	ds_bpermute_b32 v16, v221, v0
	s_waitcnt lgkmcnt(0)
	v_pk_add_f32 v[0:1], v[0:1], v[16:17]
	ds_bpermute_b32 v17, v220, v1
	ds_bpermute_b32 v16, v220, v0
	s_waitcnt lgkmcnt(0)
	v_pk_add_f32 v[0:1], v[0:1], v[16:17]
	ds_bpermute_b32 v17, v219, v1
	ds_bpermute_b32 v16, v219, v0
	s_waitcnt lgkmcnt(0)
	v_pk_add_f32 v[0:1], v[0:1], v[16:17]
	ds_bpermute_b32 v17, v218, v1
	ds_bpermute_b32 v16, v218, v0
	s_waitcnt lgkmcnt(0)
	v_pk_add_f32 v[0:1], v[0:1], v[16:17]
	ds_bpermute_b32 v17, v217, v1
	ds_bpermute_b32 v16, v217, v0
	s_waitcnt lgkmcnt(0)
; DEV bf16_t f2bf(float f) { unsigned u = __float_as_uint(f); u += 0x7fffu + ((u >> 16) & 1u); return (bf16_t)(u >> 16); }
; DEV int crow(int r, int hi) { return (r & 3) + 8 * (r >> 2) + 4 * hi; }
; template <bool SPREAD>
; DEV void attn_store(f32x16 (&o)[4], const float* __restrict__ gain, float oscale, bf16_t* __restrict__ mix, int q0, int colbase) {
;     ...
;   for (int r = 0; r < 16; ++r) {
;     float ss = o[0][r] * o[0][r] + o[1][r] * o[1][r] + o[2][r] * o[2][r] + o[3][r] * o[3][r];
;     ss += __shfl_xor(ss, 1); ss += __shfl_xor(ss, 2); ss += __shfl_xor(ss, 4); ss += __shfl_xor(ss, 8); ss += __shfl_xor(ss, 16);
;     const float rn = rsqrtf(ss * (1.f / 128.f) + EPS);
;     const int cr = crow(r, hi);
; #pragma unroll
;     for (int d = 0; d < 4; ++d) *reinterpret_cast<bf16_t*>(sc + cr * 272 + (d * 32 + r32) * 2) = f2bf(o[d][r] * rn * gn[d]);
	v_pk_add_f32 v[0:1], v[0:1], v[16:17]
	s_nop 0
	v_pk_fma_f32 v[0:1], v[0:1], s[4:5], v[64:65] op_sel_hi:[1,0,0]
	s_nop 0
	v_mul_f32_e32 v16, 0x4b800000, v1
	v_cmp_gt_f32_e64 s[0:1], s33, v1
	v_cmp_gt_f32_e32 vcc, s33, v0
	s_nop 0
	v_cndmask_b32_e64 v1, v1, v16, s[0:1]
	v_rsq_f32_e32 v1, v1
	s_nop 0
	v_mul_f32_e32 v16, 0x45800000, v1
	v_cndmask_b32_e64 v1, v1, v16, s[0:1]
	v_mul_f32_e32 v16, v50, v1
	v_mul_f32_e32 v16, v72, v16
	v_bfe_u32 v17, v16, 16, 1
	v_add3_u32 v16, v16, v17, s2
	ds_write_b16_d16_hi v73, v16 offset:544
	v_mul_f32_e32 v16, v34, v1
	v_mul_f32_e32 v16, v71, v16
	v_bfe_u32 v17, v16, 16, 1
	v_mul_f32_e32 v2, v2, v1
	v_add3_u32 v16, v16, v17, s2
	v_mul_f32_e32 v2, v70, v2
	ds_write_b16_d16_hi v73, v16 offset:608
	v_bfe_u32 v16, v2, 16, 1
	v_mul_f32_e32 v1, v18, v1
	v_add3_u32 v2, v2, v16, s2
	v_mul_f32_e32 v1, v69, v1
	ds_write_b16_d16_hi v73, v2 offset:672
	v_bfe_u32 v2, v1, 16, 1
	v_add3_u32 v1, v1, v2, s2
	ds_write_b16_d16_hi v73, v1 offset:736
	v_mul_f32_e32 v1, 0x4b800000, v0
	v_cndmask_b32_e32 v0, v0, v1, vcc
	v_rsq_f32_e32 v0, v0
	v_mov_b32_e32 v16, v37
	v_mov_b32_e32 v17, v53
	v_pk_mul_f32 v[16:17], v[16:17], v[16:17]
	v_mul_f32_e32 v1, 0x45800000, v0
	v_cndmask_b32_e32 v0, v0, v1, vcc
	v_mul_f32_e32 v1, v51, v0
	v_mul_f32_e32 v1, v72, v1
	v_bfe_u32 v2, v1, 16, 1
	v_add3_u32 v1, v1, v2, s2
	ds_write_b16_d16_hi v73, v1 offset:816
	v_mul_f32_e32 v1, v35, v0
	v_mul_f32_e32 v1, v71, v1
	v_bfe_u32 v2, v1, 16, 1
	v_add3_u32 v1, v1, v2, s2
	ds_write_b16_d16_hi v73, v1 offset:880
	v_mul_f32_e32 v1, v3, v0
	v_mul_f32_e32 v1, v70, v1
	v_bfe_u32 v2, v1, 16, 1
	v_mul_f32_e32 v0, v19, v0
	v_add3_u32 v1, v1, v2, s2
	v_mul_f32_e32 v0, v69, v0
	ds_write_b16_d16_hi v73, v1 offset:944
	v_bfe_u32 v1, v0, 16, 1
	v_add3_u32 v0, v0, v1, s2
	ds_write_b16_d16_hi v73, v0 offset:1008
	v_mov_b32_e32 v0, v36
	v_mov_b32_e32 v1, v52
	v_pk_mul_f32 v[0:1], v[0:1], v[0:1]
	v_mov_b32_e32 v2, v20
	v_mov_b32_e32 v3, v4
	v_mov_b32_e32 v18, v21
	v_mov_b32_e32 v19, v5
	v_pk_mul_f32 v[2:3], v[2:3], v[2:3]
	v_pk_mul_f32 v[18:19], v[18:19], v[18:19]
	v_mov_b32_e32 v32, v16
	v_mov_b32_e32 v33, v0
	v_mov_b32_e32 v0, v17
	v_pk_add_f32 v[0:1], v[32:33], v[0:1]
	v_mov_b32_e32 v16, v19
	v_mov_b32_e32 v17, v3
	v_pk_add_f32 v[0:1], v[16:17], v[0:1]
	v_mov_b32_e32 v19, v2
	v_pk_add_f32 v[0:1], v[18:19], v[0:1]
	ds_bpermute_b32 v3, v221, v1
	ds_bpermute_b32 v2, v221, v0
	v_mov_b32_e32 v16, v23
	v_mov_b32_e32 v17, v7
	v_pk_mul_f32 v[16:17], v[16:17], v[16:17]
	s_waitcnt lgkmcnt(0)
	v_pk_add_f32 v[0:1], v[0:1], v[2:3]
	ds_bpermute_b32 v3, v220, v1
	ds_bpermute_b32 v2, v220, v0
	s_waitcnt lgkmcnt(0)
	v_pk_add_f32 v[0:1], v[0:1], v[2:3]
	ds_bpermute_b32 v3, v219, v1
	ds_bpermute_b32 v2, v219, v0
	s_waitcnt lgkmcnt(0)
	v_pk_add_f32 v[0:1], v[0:1], v[2:3]
	ds_bpermute_b32 v3, v218, v1
	ds_bpermute_b32 v2, v218, v0
	s_waitcnt lgkmcnt(0)
	v_pk_add_f32 v[0:1], v[0:1], v[2:3]
	ds_bpermute_b32 v3, v217, v1
	ds_bpermute_b32 v2, v217, v0
	s_waitcnt lgkmcnt(0)
	v_pk_add_f32 v[0:1], v[0:1], v[2:3]
	s_nop 0
	v_pk_fma_f32 v[0:1], v[0:1], s[4:5], v[64:65] op_sel_hi:[1,0,0]
	s_nop 0
	v_mul_f32_e32 v2, 0x4b800000, v1
	v_cmp_gt_f32_e64 s[0:1], s33, v1
	v_cmp_gt_f32_e32 vcc, s33, v0
	s_nop 0
	v_cndmask_b32_e64 v1, v1, v2, s[0:1]
	v_rsq_f32_e32 v1, v1
	s_nop 0
	v_mul_f32_e32 v2, 0x45800000, v1
	v_cndmask_b32_e64 v1, v1, v2, s[0:1]
	v_mul_f32_e32 v2, v52, v1
	v_mul_f32_e32 v2, v72, v2
	v_bfe_u32 v3, v2, 16, 1
	v_add3_u32 v2, v2, v3, s2
	ds_write_b16_d16_hi v73, v2 offset:2176
	v_mul_f32_e32 v2, v36, v1
	v_mul_f32_e32 v2, v71, v2
	v_bfe_u32 v3, v2, 16, 1
	v_add3_u32 v2, v2, v3, s2
	ds_write_b16_d16_hi v73, v2 offset:2240
	v_mul_f32_e32 v2, v4, v1
	v_mul_f32_e32 v2, v70, v2
	v_bfe_u32 v3, v2, 16, 1
	v_mul_f32_e32 v1, v20, v1
	v_add3_u32 v2, v2, v3, s2
	v_mul_f32_e32 v1, v69, v1
	ds_write_b16_d16_hi v73, v2 offset:2304
	v_bfe_u32 v2, v1, 16, 1
	v_add3_u32 v1, v1, v2, s2
	ds_write_b16_d16_hi v73, v1 offset:2368
	v_mul_f32_e32 v1, 0x4b800000, v0
	v_cndmask_b32_e32 v0, v0, v1, vcc
	v_rsq_f32_e32 v0, v0
	v_mov_b32_e32 v4, v39
	v_mov_b32_e32 v3, v6
	v_mul_f32_e32 v1, 0x45800000, v0
	v_cndmask_b32_e32 v0, v0, v1, vcc
	v_mul_f32_e32 v1, v53, v0
	v_mul_f32_e32 v1, v72, v1
	v_bfe_u32 v2, v1, 16, 1
	v_add3_u32 v1, v1, v2, s2
	ds_write_b16_d16_hi v73, v1 offset:2448
	v_mul_f32_e32 v1, v37, v0
	v_mul_f32_e32 v1, v71, v1
	v_bfe_u32 v2, v1, 16, 1
	v_add3_u32 v1, v1, v2, s2
	ds_write_b16_d16_hi v73, v1 offset:2512
	v_mul_f32_e32 v1, v5, v0
	v_mul_f32_e32 v1, v70, v1
	v_bfe_u32 v2, v1, 16, 1
	v_mul_f32_e32 v0, v21, v0
	v_add3_u32 v1, v1, v2, s2
	v_mul_f32_e32 v0, v69, v0
	ds_write_b16_d16_hi v73, v1 offset:2576
	v_bfe_u32 v1, v0, 16, 1
	v_add3_u32 v0, v0, v1, s2
	ds_write_b16_d16_hi v73, v0 offset:2640
	v_mov_b32_e32 v0, v38
	v_mov_b32_e32 v1, v54
	v_mov_b32_e32 v5, v55
	v_pk_mul_f32 v[0:1], v[0:1], v[0:1]
	v_mov_b32_e32 v2, v22
	v_pk_mul_f32 v[4:5], v[4:5], v[4:5]
	v_pk_mul_f32 v[2:3], v[2:3], v[2:3]
	v_mov_b32_e32 v18, v4
	v_mov_b32_e32 v19, v0
	v_mov_b32_e32 v0, v5
	v_pk_add_f32 v[0:1], v[18:19], v[0:1]
	v_mov_b32_e32 v4, v17
	v_mov_b32_e32 v5, v3
	v_pk_add_f32 v[0:1], v[4:5], v[0:1]
	v_mov_b32_e32 v17, v2
	v_pk_add_f32 v[0:1], v[16:17], v[0:1]
	ds_bpermute_b32 v3, v221, v1
	ds_bpermute_b32 v2, v221, v0
	v_mov_b32_e32 v4, v41
	v_mov_b32_e32 v5, v57
	v_pk_mul_f32 v[4:5], v[4:5], v[4:5]
	s_waitcnt lgkmcnt(0)
	v_pk_add_f32 v[0:1], v[0:1], v[2:3]
	ds_bpermute_b32 v3, v220, v1
	ds_bpermute_b32 v2, v220, v0
	v_mov_b32_e32 v16, v4
	s_waitcnt lgkmcnt(0)
	v_pk_add_f32 v[0:1], v[0:1], v[2:3]
	ds_bpermute_b32 v3, v219, v1
	ds_bpermute_b32 v2, v219, v0
	s_waitcnt lgkmcnt(0)
; DEV bf16_t f2bf(float f) { unsigned u = __float_as_uint(f); u += 0x7fffu + ((u >> 16) & 1u); return (bf16_t)(u >> 16); }
; DEV int crow(int r, int hi) { return (r & 3) + 8 * (r >> 2) + 4 * hi; }
; template <bool SPREAD>
; DEV void attn_store(f32x16 (&o)[4], const float* __restrict__ gain, float oscale, bf16_t* __restrict__ mix, int q0, int colbase) {
;     ...
;   for (int r = 0; r < 16; ++r) {
;     float ss = o[0][r] * o[0][r] + o[1][r] * o[1][r] + o[2][r] * o[2][r] + o[3][r] * o[3][r];
;     ss += __shfl_xor(ss, 1); ss += __shfl_xor(ss, 2); ss += __shfl_xor(ss, 4); ss += __shfl_xor(ss, 8); ss += __shfl_xor(ss, 16);
;     const float rn = rsqrtf(ss * (1.f / 128.f) + EPS);
;     const int cr = crow(r, hi);
; #pragma unroll
;     for (int d = 0; d < 4; ++d) *reinterpret_cast<bf16_t*>(sc + cr * 272 + (d * 32 + r32) * 2) = f2bf(o[d][r] * rn * gn[d]);
	v_pk_add_f32 v[0:1], v[0:1], v[2:3]
	ds_bpermute_b32 v3, v218, v1
	ds_bpermute_b32 v2, v218, v0
	s_waitcnt lgkmcnt(0)
	v_pk_add_f32 v[0:1], v[0:1], v[2:3]
	ds_bpermute_b32 v3, v217, v1
	ds_bpermute_b32 v2, v217, v0
	s_waitcnt lgkmcnt(0)
	v_pk_add_f32 v[0:1], v[0:1], v[2:3]
	s_nop 0
	v_pk_fma_f32 v[0:1], v[0:1], s[4:5], v[64:65] op_sel_hi:[1,0,0]
	s_nop 0
	v_mul_f32_e32 v2, 0x4b800000, v1
	v_cmp_gt_f32_e64 s[0:1], s33, v1
	v_cmp_gt_f32_e32 vcc, s33, v0
	s_nop 0
	v_cndmask_b32_e64 v1, v1, v2, s[0:1]
	v_rsq_f32_e32 v1, v1
	s_nop 0
	v_mul_f32_e32 v2, 0x45800000, v1
	v_cndmask_b32_e64 v1, v1, v2, s[0:1]
	v_mul_f32_e32 v2, v54, v1
	v_mul_f32_e32 v2, v72, v2
	v_bfe_u32 v3, v2, 16, 1
	v_add3_u32 v2, v2, v3, s2
	ds_write_b16_d16_hi v73, v2 offset:2720
	v_mul_f32_e32 v2, v38, v1
	v_mul_f32_e32 v2, v71, v2
	v_bfe_u32 v3, v2, 16, 1
	v_add3_u32 v2, v2, v3, s2
	ds_write_b16_d16_hi v73, v2 offset:2784
	v_mul_f32_e32 v2, v6, v1
	v_mul_f32_e32 v2, v70, v2
	v_bfe_u32 v3, v2, 16, 1
	v_mul_f32_e32 v1, v22, v1
	v_add3_u32 v2, v2, v3, s2
	v_mul_f32_e32 v1, v69, v1
	ds_write_b16_d16_hi v73, v2 offset:2848
	v_bfe_u32 v2, v1, 16, 1
	v_add3_u32 v1, v1, v2, s2
	ds_write_b16_d16_hi v73, v1 offset:2912
	v_mul_f32_e32 v1, 0x4b800000, v0
	v_cndmask_b32_e32 v0, v0, v1, vcc
	v_rsq_f32_e32 v0, v0
	v_mov_b32_e32 v3, v8
	v_mov_b32_e32 v6, v25
	v_mul_f32_e32 v1, 0x45800000, v0
	v_cndmask_b32_e32 v0, v0, v1, vcc
	v_mul_f32_e32 v1, v55, v0
	v_mul_f32_e32 v1, v72, v1
	v_bfe_u32 v2, v1, 16, 1
	v_add3_u32 v1, v1, v2, s2
	ds_write_b16_d16_hi v73, v1 offset:2992
	v_mul_f32_e32 v1, v39, v0
	v_mul_f32_e32 v1, v71, v1
	v_bfe_u32 v2, v1, 16, 1
	v_add3_u32 v1, v1, v2, s2
	ds_write_b16_d16_hi v73, v1 offset:3056
	v_mul_f32_e32 v1, v7, v0
	v_mul_f32_e32 v1, v70, v1
	v_bfe_u32 v2, v1, 16, 1
	v_mul_f32_e32 v0, v23, v0
	v_add3_u32 v1, v1, v2, s2
	v_mul_f32_e32 v0, v69, v0
	ds_write_b16_d16_hi v73, v1 offset:3120
	v_bfe_u32 v1, v0, 16, 1
	v_add3_u32 v0, v0, v1, s2
	ds_write_b16_d16_hi v73, v0 offset:3184
	v_mov_b32_e32 v0, v40
	v_mov_b32_e32 v1, v56
	v_pk_mul_f32 v[0:1], v[0:1], v[0:1]
	v_mov_b32_e32 v2, v24
	v_mov_b32_e32 v7, v9
	v_pk_mul_f32 v[2:3], v[2:3], v[2:3]
	v_pk_mul_f32 v[6:7], v[6:7], v[6:7]
	v_mov_b32_e32 v17, v0
	v_mov_b32_e32 v0, v5
	v_pk_add_f32 v[0:1], v[16:17], v[0:1]
	v_mov_b32_e32 v4, v7
	v_mov_b32_e32 v5, v3
	v_pk_add_f32 v[0:1], v[4:5], v[0:1]
	v_mov_b32_e32 v7, v2
	v_pk_add_f32 v[0:1], v[6:7], v[0:1]
	ds_bpermute_b32 v3, v221, v1
	ds_bpermute_b32 v2, v221, v0
	v_mov_b32_e32 v4, v43
	v_mov_b32_e32 v5, v59
	v_pk_mul_f32 v[4:5], v[4:5], v[4:5]
	v_mov_b32_e32 v6, v27
	s_waitcnt lgkmcnt(0)
	v_pk_add_f32 v[0:1], v[0:1], v[2:3]
	ds_bpermute_b32 v3, v220, v1
	ds_bpermute_b32 v2, v220, v0
	v_mov_b32_e32 v7, v11
	v_pk_mul_f32 v[6:7], v[6:7], v[6:7]
	v_mov_b32_e32 v17, 0x2000
	s_waitcnt lgkmcnt(0)
	v_pk_add_f32 v[0:1], v[0:1], v[2:3]
	ds_bpermute_b32 v3, v219, v1
	ds_bpermute_b32 v2, v219, v0
	s_waitcnt lgkmcnt(0)
	v_pk_add_f32 v[0:1], v[0:1], v[2:3]
	ds_bpermute_b32 v3, v218, v1
	ds_bpermute_b32 v2, v218, v0
	s_waitcnt lgkmcnt(0)
	v_pk_add_f32 v[0:1], v[0:1], v[2:3]
	ds_bpermute_b32 v3, v217, v1
	ds_bpermute_b32 v2, v217, v0
	s_waitcnt lgkmcnt(0)
	v_pk_add_f32 v[0:1], v[0:1], v[2:3]
	s_nop 0
	v_pk_fma_f32 v[0:1], v[0:1], s[4:5], v[64:65] op_sel_hi:[1,0,0]
	s_nop 0
	v_mul_f32_e32 v2, 0x4b800000, v1
	v_cmp_gt_f32_e64 s[0:1], s33, v1
	v_cmp_gt_f32_e32 vcc, s33, v0
	s_nop 0
	v_cndmask_b32_e64 v1, v1, v2, s[0:1]
	v_rsq_f32_e32 v1, v1
	s_nop 0
	v_mul_f32_e32 v2, 0x45800000, v1
	v_cndmask_b32_e64 v1, v1, v2, s[0:1]
	v_mul_f32_e32 v2, v56, v1
	v_mul_f32_e32 v2, v72, v2
	v_bfe_u32 v3, v2, 16, 1
	v_add3_u32 v2, v2, v3, s2
	ds_write_b16_d16_hi v73, v2 offset:4352
	v_mul_f32_e32 v2, v40, v1
	v_mul_f32_e32 v2, v71, v2
	v_bfe_u32 v3, v2, 16, 1
	v_add3_u32 v2, v2, v3, s2
	ds_write_b16_d16_hi v73, v2 offset:4416
	v_mul_f32_e32 v2, v8, v1
	v_mul_f32_e32 v2, v70, v2
	v_bfe_u32 v3, v2, 16, 1
	v_mul_f32_e32 v1, v24, v1
	v_add3_u32 v2, v2, v3, s2
	v_mul_f32_e32 v1, v69, v1
	ds_write_b16_d16_hi v73, v2 offset:4480
	v_bfe_u32 v2, v1, 16, 1
	v_add3_u32 v1, v1, v2, s2
	ds_write_b16_d16_hi v73, v1 offset:4544
	v_mul_f32_e32 v1, 0x4b800000, v0
	v_cndmask_b32_e32 v0, v0, v1, vcc
	v_rsq_f32_e32 v0, v0
	v_mov_b32_e32 v3, v10
	v_mov_b32_e32 v8, v4
	v_mov_b32_e32 v4, v7
	v_mul_f32_e32 v1, 0x45800000, v0
	v_cndmask_b32_e32 v0, v0, v1, vcc
	v_mul_f32_e32 v1, v57, v0
	v_mul_f32_e32 v1, v72, v1
	v_bfe_u32 v2, v1, 16, 1
	v_add3_u32 v1, v1, v2, s2
	ds_write_b16_d16_hi v73, v1 offset:4624
	v_mul_f32_e32 v1, v41, v0
	v_mul_f32_e32 v1, v71, v1
	v_bfe_u32 v2, v1, 16, 1
	v_add3_u32 v1, v1, v2, s2
	ds_write_b16_d16_hi v73, v1 offset:4688
	v_mul_f32_e32 v1, v9, v0
	v_mul_f32_e32 v1, v70, v1
	v_bfe_u32 v2, v1, 16, 1
	v_mul_f32_e32 v0, v25, v0
	v_add3_u32 v1, v1, v2, s2
	v_mul_f32_e32 v0, v69, v0
	ds_write_b16_d16_hi v73, v1 offset:4752
	v_bfe_u32 v1, v0, 16, 1
	v_add3_u32 v0, v0, v1, s2
	ds_write_b16_d16_hi v73, v0 offset:4816
	v_mov_b32_e32 v0, v42
	v_mov_b32_e32 v1, v58
	v_pk_mul_f32 v[0:1], v[0:1], v[0:1]
	v_mov_b32_e32 v2, v26
	v_pk_mul_f32 v[2:3], v[2:3], v[2:3]
	v_mov_b32_e32 v9, v0
	v_mov_b32_e32 v0, v5
	v_pk_add_f32 v[0:1], v[8:9], v[0:1]
	v_mov_b32_e32 v5, v3
	v_pk_add_f32 v[0:1], v[4:5], v[0:1]
	v_mov_b32_e32 v7, v2
	v_pk_add_f32 v[0:1], v[6:7], v[0:1]
	ds_bpermute_b32 v3, v221, v1
	ds_bpermute_b32 v2, v221, v0
	v_mov_b32_e32 v4, v45
	v_mov_b32_e32 v5, v61
	v_pk_mul_f32 v[4:5], v[4:5], v[4:5]
	v_mov_b32_e32 v6, v29
	s_waitcnt lgkmcnt(0)
	v_pk_add_f32 v[0:1], v[0:1], v[2:3]
	ds_bpermute_b32 v3, v220, v1
	ds_bpermute_b32 v2, v220, v0
	v_mov_b32_e32 v7, v13
	v_pk_mul_f32 v[6:7], v[6:7], v[6:7]
	v_mov_b32_e32 v8, v4
	v_mov_b32_e32 v4, v7
	s_waitcnt lgkmcnt(0)
; DEV bf16_t f2bf(float f) { unsigned u = __float_as_uint(f); u += 0x7fffu + ((u >> 16) & 1u); return (bf16_t)(u >> 16); }
; DEV int crow(int r, int hi) { return (r & 3) + 8 * (r >> 2) + 4 * hi; }
; template <bool SPREAD>
; DEV void attn_store(f32x16 (&o)[4], const float* __restrict__ gain, float oscale, bf16_t* __restrict__ mix, int q0, int colbase) {
;     ...
;   for (int r = 0; r < 16; ++r) {
;     float ss = o[0][r] * o[0][r] + o[1][r] * o[1][r] + o[2][r] * o[2][r] + o[3][r] * o[3][r];
;     ss += __shfl_xor(ss, 1); ss += __shfl_xor(ss, 2); ss += __shfl_xor(ss, 4); ss += __shfl_xor(ss, 8); ss += __shfl_xor(ss, 16);
;     const float rn = rsqrtf(ss * (1.f / 128.f) + EPS);
;     const int cr = crow(r, hi);
; #pragma unroll
;     for (int d = 0; d < 4; ++d) *reinterpret_cast<bf16_t*>(sc + cr * 272 + (d * 32 + r32) * 2) = f2bf(o[d][r] * rn * gn[d]);
	v_pk_add_f32 v[0:1], v[0:1], v[2:3]
	ds_bpermute_b32 v3, v219, v1
	ds_bpermute_b32 v2, v219, v0
	s_waitcnt lgkmcnt(0)
	v_pk_add_f32 v[0:1], v[0:1], v[2:3]
	ds_bpermute_b32 v3, v218, v1
	ds_bpermute_b32 v2, v218, v0
	s_waitcnt lgkmcnt(0)
	v_pk_add_f32 v[0:1], v[0:1], v[2:3]
	ds_bpermute_b32 v3, v217, v1
	ds_bpermute_b32 v2, v217, v0
	s_waitcnt lgkmcnt(0)
	v_pk_add_f32 v[0:1], v[0:1], v[2:3]
	s_nop 0
	v_pk_fma_f32 v[0:1], v[0:1], s[4:5], v[64:65] op_sel_hi:[1,0,0]
	s_nop 0
	v_mul_f32_e32 v2, 0x4b800000, v1
	v_cmp_gt_f32_e64 s[0:1], s33, v1
	v_cmp_gt_f32_e32 vcc, s33, v0
	s_nop 0
	v_cndmask_b32_e64 v1, v1, v2, s[0:1]
	v_rsq_f32_e32 v1, v1
	s_nop 0
	v_mul_f32_e32 v2, 0x45800000, v1
	v_cndmask_b32_e64 v1, v1, v2, s[0:1]
	v_mul_f32_e32 v2, v58, v1
	v_mul_f32_e32 v2, v72, v2
	v_bfe_u32 v3, v2, 16, 1
	v_add3_u32 v2, v2, v3, s2
	ds_write_b16_d16_hi v73, v2 offset:4896
	v_mul_f32_e32 v2, v42, v1
	v_mul_f32_e32 v2, v71, v2
	v_bfe_u32 v3, v2, 16, 1
	v_add3_u32 v2, v2, v3, s2
	ds_write_b16_d16_hi v73, v2 offset:4960
	v_mul_f32_e32 v2, v10, v1
	v_mul_f32_e32 v2, v70, v2
	v_bfe_u32 v3, v2, 16, 1
	v_mul_f32_e32 v1, v26, v1
	v_add3_u32 v2, v2, v3, s2
	v_mul_f32_e32 v1, v69, v1
	ds_write_b16_d16_hi v73, v2 offset:5024
	v_bfe_u32 v2, v1, 16, 1
	v_add3_u32 v1, v1, v2, s2
	ds_write_b16_d16_hi v73, v1 offset:5088
	v_mul_f32_e32 v1, 0x4b800000, v0
	v_cndmask_b32_e32 v0, v0, v1, vcc
	v_rsq_f32_e32 v0, v0
	v_mov_b32_e32 v3, v12
	v_mul_f32_e32 v1, 0x45800000, v0
	v_cndmask_b32_e32 v0, v0, v1, vcc
	v_mul_f32_e32 v1, v59, v0
	v_mul_f32_e32 v1, v72, v1
	v_bfe_u32 v2, v1, 16, 1
	v_add3_u32 v1, v1, v2, s2
	ds_write_b16_d16_hi v73, v1 offset:5168
	v_mul_f32_e32 v1, v43, v0
	v_mul_f32_e32 v1, v71, v1
	v_bfe_u32 v2, v1, 16, 1
	v_add3_u32 v1, v1, v2, s2
	ds_write_b16_d16_hi v73, v1 offset:5232
	v_mul_f32_e32 v1, v11, v0
	v_mul_f32_e32 v1, v70, v1
	v_bfe_u32 v2, v1, 16, 1
	v_mul_f32_e32 v0, v27, v0
	v_add3_u32 v1, v1, v2, s2
	v_mul_f32_e32 v0, v69, v0
	ds_write_b16_d16_hi v73, v1 offset:5296
	v_bfe_u32 v1, v0, 16, 1
	v_add3_u32 v0, v0, v1, s2
	ds_write_b16_d16_hi v73, v0 offset:5360
	v_mov_b32_e32 v0, v44
	v_mov_b32_e32 v1, v60
	v_pk_mul_f32 v[0:1], v[0:1], v[0:1]
	v_mov_b32_e32 v2, v28
	v_pk_mul_f32 v[2:3], v[2:3], v[2:3]
	v_mov_b32_e32 v9, v0
	v_mov_b32_e32 v0, v5
	v_pk_add_f32 v[0:1], v[8:9], v[0:1]
	v_mov_b32_e32 v5, v3
	v_pk_add_f32 v[0:1], v[4:5], v[0:1]
	v_mov_b32_e32 v7, v2
	v_pk_add_f32 v[0:1], v[6:7], v[0:1]
	ds_bpermute_b32 v3, v221, v1
	ds_bpermute_b32 v2, v221, v0
	v_mov_b32_e32 v4, v47
	v_mov_b32_e32 v5, v63
	v_pk_mul_f32 v[4:5], v[4:5], v[4:5]
	v_mov_b32_e32 v6, v31
	s_waitcnt lgkmcnt(0)
	v_pk_add_f32 v[0:1], v[0:1], v[2:3]
	ds_bpermute_b32 v3, v220, v1
	ds_bpermute_b32 v2, v220, v0
	v_mov_b32_e32 v7, v15
	v_pk_mul_f32 v[6:7], v[6:7], v[6:7]
	v_mov_b32_e32 v8, v4
	v_mov_b32_e32 v4, v7
	s_waitcnt lgkmcnt(0)
	v_pk_add_f32 v[0:1], v[0:1], v[2:3]
	ds_bpermute_b32 v3, v219, v1
	ds_bpermute_b32 v2, v219, v0
	s_waitcnt lgkmcnt(0)
	v_pk_add_f32 v[0:1], v[0:1], v[2:3]
	ds_bpermute_b32 v3, v218, v1
	ds_bpermute_b32 v2, v218, v0
	s_waitcnt lgkmcnt(0)
	v_pk_add_f32 v[0:1], v[0:1], v[2:3]
	ds_bpermute_b32 v3, v217, v1
	ds_bpermute_b32 v2, v217, v0
	s_waitcnt lgkmcnt(0)
	v_pk_add_f32 v[0:1], v[0:1], v[2:3]
	s_nop 0
	v_pk_fma_f32 v[0:1], v[0:1], s[4:5], v[64:65] op_sel_hi:[1,0,0]
	s_nop 0
	v_mul_f32_e32 v2, 0x4b800000, v1
	v_cmp_gt_f32_e64 s[0:1], s33, v1
	v_cmp_gt_f32_e32 vcc, s33, v0
	s_nop 0
	v_cndmask_b32_e64 v1, v1, v2, s[0:1]
	v_rsq_f32_e32 v1, v1
	s_nop 0
	v_mul_f32_e32 v2, 0x45800000, v1
	v_cndmask_b32_e64 v1, v1, v2, s[0:1]
	v_mul_f32_e32 v2, v60, v1
	v_mul_f32_e32 v2, v72, v2
	v_bfe_u32 v3, v2, 16, 1
	v_add3_u32 v2, v2, v3, s2
	ds_write_b16_d16_hi v73, v2 offset:6528
	v_mul_f32_e32 v2, v44, v1
	v_mul_f32_e32 v2, v71, v2
	v_bfe_u32 v3, v2, 16, 1
	v_add3_u32 v2, v2, v3, s2
	ds_write_b16_d16_hi v73, v2 offset:6592
	v_mul_f32_e32 v2, v12, v1
	v_mul_f32_e32 v2, v70, v2
	v_bfe_u32 v3, v2, 16, 1
	v_mul_f32_e32 v1, v28, v1
	v_add3_u32 v2, v2, v3, s2
	v_mul_f32_e32 v1, v69, v1
	ds_write_b16_d16_hi v73, v2 offset:6656
	v_bfe_u32 v2, v1, 16, 1
	v_add3_u32 v1, v1, v2, s2
	ds_write_b16_d16_hi v73, v1 offset:6720
	v_mul_f32_e32 v1, 0x4b800000, v0
	v_cndmask_b32_e32 v0, v0, v1, vcc
	v_rsq_f32_e32 v0, v0
	v_mov_b32_e32 v3, v14
	v_mul_f32_e32 v1, 0x45800000, v0
	v_cndmask_b32_e32 v0, v0, v1, vcc
	v_mul_f32_e32 v1, v61, v0
	v_mul_f32_e32 v1, v72, v1
	v_bfe_u32 v2, v1, 16, 1
	v_add3_u32 v1, v1, v2, s2
	ds_write_b16_d16_hi v73, v1 offset:6800
	v_mul_f32_e32 v1, v45, v0
	v_mul_f32_e32 v1, v71, v1
	v_bfe_u32 v2, v1, 16, 1
	v_add3_u32 v1, v1, v2, s2
	ds_write_b16_d16_hi v73, v1 offset:6864
	v_mul_f32_e32 v1, v13, v0
	v_mul_f32_e32 v1, v70, v1
	v_bfe_u32 v2, v1, 16, 1
	v_mul_f32_e32 v0, v29, v0
	v_add3_u32 v1, v1, v2, s2
	v_mul_f32_e32 v0, v69, v0
	ds_write_b16_d16_hi v73, v1 offset:6928
	v_bfe_u32 v1, v0, 16, 1
	v_add3_u32 v0, v0, v1, s2
	ds_write_b16_d16_hi v73, v0 offset:6992
	v_mov_b32_e32 v0, v46
	v_mov_b32_e32 v1, v62
	v_pk_mul_f32 v[0:1], v[0:1], v[0:1]
	v_mov_b32_e32 v2, v30
	v_pk_mul_f32 v[2:3], v[2:3], v[2:3]
	v_mov_b32_e32 v9, v0
	v_mov_b32_e32 v0, v5
	v_pk_add_f32 v[0:1], v[8:9], v[0:1]
	v_mov_b32_e32 v5, v3
	v_pk_add_f32 v[0:1], v[4:5], v[0:1]
	v_mov_b32_e32 v7, v2
	v_pk_add_f32 v[0:1], v[6:7], v[0:1]
	ds_bpermute_b32 v3, v221, v1
	ds_bpermute_b32 v2, v221, v0
	v_bfe_u32 v6, v66, 4, 2
	v_lshl_add_u32 v7, v67, 5, s74
	s_waitcnt lgkmcnt(0)
	v_pk_add_f32 v[0:1], v[0:1], v[2:3]
	ds_bpermute_b32 v3, v220, v1
	ds_bpermute_b32 v2, v220, v0
	s_waitcnt lgkmcnt(0)
	v_pk_add_f32 v[0:1], v[0:1], v[2:3]
	ds_bpermute_b32 v3, v219, v1
	ds_bpermute_b32 v2, v219, v0
	s_waitcnt lgkmcnt(0)
; DEV bf16_t f2bf(float f) { unsigned u = __float_as_uint(f); u += 0x7fffu + ((u >> 16) & 1u); return (bf16_t)(u >> 16); }
; DEV int lv(int x) { asm volatile("" : "+v"(x)); return x; }
; DEV int crow(int r, int hi) { return (r & 3) + 8 * (r >> 2) + 4 * hi; }
; DEV void diff16_pass(const bf16_t* __restrict__ proj, int qcol, int kcol, int vcol, int q0, f32x4 (&o)[2][8], f32x4 (&l_out)[2], unsigned char* lds) {
;   const int tid = lv(threadIdx.x), wid = tid >> 6, lane = tid & 63, fr = lane & 15, fq = lane >> 4;
;   float* al_l = (float*)(lds + D_WSF) + wid * 64 + 32;
;   const lds_cptr qrd = (lds_cptr)shm_raw + D_QOFF + wid * 4096 + lane * 16;
; #pragma unroll
;   for (int g = 0; g < 2; ++g) { const int sl = 16 * g + fr; const bf16_t* Qw = proj + (size_t)(q0 + 64 * (sl >> 3) + 8 * wid + (sl & 7)) * INW + qcol + fq * 8;
;     *reinterpret_cast<bf16x8*>(lds + D_QOFF + wid * 4096 + (g * 2 + 0) * 1024 + lane * 16) = *reinterpret_cast<const bf16x8*>(Qw);
;     *reinterpret_cast<bf16x8*>(lds + D_QOFF + wid * 4096 + (g * 2 + 1) * 1024 + lane * 16) = *reinterpret_cast<const bf16x8*>(Qw + 32); }
; template <bool SPREAD>
; DEV void attn_store(f32x16 (&o)[4], const float* __restrict__ gain, float oscale, bf16_t* __restrict__ mix, int q0, int colbase) {
;     ...
;   for (int r = 0; r < 16; ++r) {
;     float ss = o[0][r] * o[0][r] + o[1][r] * o[1][r] + o[2][r] * o[2][r] + o[3][r] * o[3][r];
;     ss += __shfl_xor(ss, 1); ss += __shfl_xor(ss, 2); ss += __shfl_xor(ss, 4); ss += __shfl_xor(ss, 8); ss += __shfl_xor(ss, 16);
;     const float rn = rsqrtf(ss * (1.f / 128.f) + EPS);
;     const int cr = crow(r, hi);
; #pragma unroll
;     for (int d = 0; d < 4; ++d) *reinterpret_cast<bf16_t*>(sc + cr * 272 + (d * 32 + r32) * 2) = f2bf(o[d][r] * rn * gn[d]);
;   }
; #pragma unroll
;   for (int i = 0; i < 8; ++i) { const int rs = 4 * i + (lane >> 4);
;     const u32x4 w = *reinterpret_cast<const u32x4*>(sc + rs * 272 + (lane & 15) * 16);
;     const size_t row = SPREAD ? (size_t)(q0 + 64 * (rs >> 3) + 8 * wid + (rs & 7)) : (size_t)(q0 + wid * 32 + rs);
;     *reinterpret_cast<u32x4*>(mix + row * DM + colbase + (lane & 15) * 8) = w; }
;   __syncthreads();
	v_pk_add_f32 v[0:1], v[0:1], v[2:3]
	ds_bpermute_b32 v3, v218, v1
	ds_bpermute_b32 v2, v218, v0
	s_waitcnt lgkmcnt(0)
	v_pk_add_f32 v[0:1], v[0:1], v[2:3]
	ds_bpermute_b32 v3, v217, v1
	ds_bpermute_b32 v2, v217, v0
	s_waitcnt lgkmcnt(0)
	v_pk_add_f32 v[0:1], v[0:1], v[2:3]
	s_nop 0
	v_pk_fma_f32 v[0:1], v[0:1], s[4:5], v[64:65] op_sel_hi:[1,0,0]
	s_nop 0
	v_mul_f32_e32 v2, 0x4b800000, v1
	v_cmp_gt_f32_e64 s[0:1], s33, v1
	v_cmp_gt_f32_e32 vcc, s33, v0
	s_nop 0
	v_cndmask_b32_e64 v1, v1, v2, s[0:1]
	v_rsq_f32_e32 v1, v1
	s_nop 0
	v_mul_f32_e32 v2, 0x45800000, v1
	v_cndmask_b32_e64 v1, v1, v2, s[0:1]
	v_mul_f32_e32 v2, v62, v1
	v_mul_f32_e32 v2, v72, v2
	v_bfe_u32 v3, v2, 16, 1
	v_add3_u32 v2, v2, v3, s2
	ds_write_b16_d16_hi v73, v2 offset:7072
	v_mul_f32_e32 v2, v46, v1
	v_mul_f32_e32 v2, v71, v2
	v_bfe_u32 v3, v2, 16, 1
	v_add3_u32 v2, v2, v3, s2
	ds_write_b16_d16_hi v73, v2 offset:7136
	v_mul_f32_e32 v2, v14, v1
	v_mul_f32_e32 v2, v70, v2
	v_bfe_u32 v3, v2, 16, 1
	v_mul_f32_e32 v1, v30, v1
	v_add3_u32 v2, v2, v3, s2
	v_mul_f32_e32 v1, v69, v1
	ds_write_b16_d16_hi v73, v2 offset:7200
	v_bfe_u32 v2, v1, 16, 1
	v_add3_u32 v1, v1, v2, s2
	ds_write_b16_d16_hi v73, v1 offset:7264
	v_mul_f32_e32 v1, 0x4b800000, v0
	v_cndmask_b32_e32 v0, v0, v1, vcc
	v_rsq_f32_e32 v0, v0
	v_readlane_b32 s0, v255, 47
	v_readlane_b32 s1, v255, 48
	v_mul_f32_e32 v1, 0x45800000, v0
	v_cndmask_b32_e32 v0, v0, v1, vcc
	v_mul_f32_e32 v1, v63, v0
	v_mul_f32_e32 v1, v72, v1
	v_bfe_u32 v2, v1, 16, 1
	v_add3_u32 v1, v1, v2, s2
	ds_write_b16_d16_hi v73, v1 offset:7344
	v_mul_f32_e32 v1, v47, v0
	v_mul_f32_e32 v1, v71, v1
	v_bfe_u32 v2, v1, 16, 1
	v_add3_u32 v1, v1, v2, s2
	ds_write_b16_d16_hi v73, v1 offset:7408
	v_mul_f32_e32 v1, v15, v0
	v_mul_f32_e32 v1, v70, v1
	v_bfe_u32 v2, v1, 16, 1
	v_mul_f32_e32 v0, v31, v0
	v_add3_u32 v1, v1, v2, s2
	v_mul_f32_e32 v0, v69, v0
	ds_write_b16_d16_hi v73, v1 offset:7472
	v_bfe_u32 v1, v0, 16, 1
	v_add3_u32 v0, v0, v1, s2
	ds_write_b16_d16_hi v73, v0 offset:7536
	v_lshlrev_b32_e32 v0, 4, v66
	v_and_b32_e32 v192, 0xf0, v0
	v_mul_u32_u24_e32 v0, 0x110, v6
	v_add3_u32 v10, v68, v192, v0
	ds_read_b128 v[0:3], v10
	v_or_b32_e32 v6, v7, v6
	v_ashrrev_i32_e32 v7, 31, v6
	v_lshl_add_u64 v[4:5], s[0:1], 0, v[192:193]
	v_lshlrev_b64 v[8:9], 12, v[6:7]
	v_lshl_add_u64 v[8:9], v[4:5], 0, v[8:9]
	s_waitcnt lgkmcnt(0)
	global_store_dwordx4 v[8:9], v[0:3], off
	ds_read_b128 v[0:3], v10 offset:1088
	v_or_b32_e32 v8, 4, v6
	v_ashrrev_i32_e32 v9, 31, v8
	v_lshlrev_b64 v[8:9], 12, v[8:9]
	v_lshl_add_u64 v[8:9], v[4:5], 0, v[8:9]
	s_waitcnt lgkmcnt(0)
	global_store_dwordx4 v[8:9], v[0:3], off
	ds_read_b128 v[0:3], v10 offset:2176
	v_or_b32_e32 v8, 8, v6
	v_ashrrev_i32_e32 v9, 31, v8
	v_lshlrev_b64 v[8:9], 12, v[8:9]
	v_lshl_add_u64 v[8:9], v[4:5], 0, v[8:9]
	s_waitcnt lgkmcnt(0)
	global_store_dwordx4 v[8:9], v[0:3], off
	ds_read_b128 v[0:3], v10 offset:3264
	v_or_b32_e32 v8, 12, v6
	v_ashrrev_i32_e32 v9, 31, v8
	v_lshlrev_b64 v[8:9], 12, v[8:9]
	v_lshl_add_u64 v[8:9], v[4:5], 0, v[8:9]
	s_waitcnt lgkmcnt(0)
	global_store_dwordx4 v[8:9], v[0:3], off
	ds_read_b128 v[0:3], v10 offset:4352
	v_or_b32_e32 v8, 16, v6
	v_ashrrev_i32_e32 v9, 31, v8
	v_lshlrev_b64 v[8:9], 12, v[8:9]
	v_lshl_add_u64 v[8:9], v[4:5], 0, v[8:9]
	s_waitcnt lgkmcnt(0)
	global_store_dwordx4 v[8:9], v[0:3], off
	ds_read_b128 v[0:3], v10 offset:5440
	v_or_b32_e32 v8, 20, v6
	v_ashrrev_i32_e32 v9, 31, v8
	v_lshlrev_b64 v[8:9], 12, v[8:9]
	v_lshl_add_u64 v[8:9], v[4:5], 0, v[8:9]
	s_waitcnt lgkmcnt(0)
	global_store_dwordx4 v[8:9], v[0:3], off
	ds_read_b128 v[0:3], v10 offset:6528
	v_or_b32_e32 v8, 24, v6
	v_ashrrev_i32_e32 v9, 31, v8
	v_lshlrev_b64 v[8:9], 12, v[8:9]
	v_lshl_add_u64 v[8:9], v[4:5], 0, v[8:9]
	s_waitcnt lgkmcnt(0)
	global_store_dwordx4 v[8:9], v[0:3], off
	ds_read_b128 v[0:3], v10 offset:7616
	v_or_b32_e32 v6, 28, v6
	v_ashrrev_i32_e32 v7, 31, v6
	v_lshlrev_b64 v[6:7], 12, v[6:7]
	v_lshl_add_u64 v[4:5], v[4:5], 0, v[6:7]
	v_mov_b32_e32 v8, v210
	s_waitcnt lgkmcnt(0)
	global_store_dwordx4 v[4:5], v[0:3], off
	s_barrier
	v_readlane_b32 s0, v255, 51
	v_ashrrev_i32_e32 v9, 6, v8
	v_and_b32_e32 v0, 0x3fffffc0, v8
	v_lshlrev_b32_e32 v12, 3, v8
	v_and_b32_e32 v13, 7, v8
	v_lshl_add_u32 v225, v0, 2, s16
	v_and_b32_e32 v0, 64, v12
	v_lshlrev_b32_e32 v1, 3, v9
	v_or_b32_e32 v2, s74, v13
	v_and_b32_e32 v192, 48, v8
	v_readlane_b32 s1, v255, 52
	v_add3_u32 v14, v2, v1, v0
	v_and_b32_e32 v227, 63, v8
	v_lshl_add_u64 v[4:5], s[0:1], 0, v[192:193]
	v_readlane_b32 s0, v255, 10
	v_lshlrev_b32_e32 v11, 4, v227
	v_bfe_u32 v10, v8, 4, 2
	v_lshl_add_u32 v15, v9, 12, s0
	v_mad_i64_i32 v[6:7], s[0:1], v14, s85, v[4:5]
	global_load_dwordx4 v[0:3], v[6:7], off
	global_load_dwordx4 v[96:99], v[6:7], off offset:64
	v_add_u32_e32 v108, 0x80, v14
	v_mad_i64_i32 v[4:5], s[0:1], v108, s85, v[4:5]
	global_load_dwordx4 v[100:103], v[4:5], off
	global_load_dwordx4 v[104:107], v[4:5], off offset:64
	v_add_u32_e32 v228, v15, v11
	v_lshrrev_b32_e32 v15, 6, v8
	v_and_b32_e32 v15, 4, v15
	v_lshl_add_u32 v17, v8, 4, v17
	v_lshrrev_b32_e32 v17, 8, v17
	v_and_b32_e32 v226, 15, v8
	s_waitcnt vmcnt(0)
; #define VWAIT(n) asm volatile("s_waitcnt vmcnt(" #n ")" ::: "memory")
; #define LBAR() do { asm volatile("s_waitcnt lgkmcnt(0)" ::: "memory"); __builtin_amdgcn_s_barrier(); } while (0)
; #define VWAIT(n) asm volatile("s_waitcnt vmcnt(" #n ")" ::: "memory")
; #define LBAR() do { asm volatile("s_waitcnt lgkmcnt(0)" ::: "memory"); __builtin_amdgcn_s_barrier(); } while (0)
; #define ROWMAXF16(S, pm) do { _Pragma("unroll") for (int g = 0; g < 2; ++g) { float m_ = S[g][0][0]; \
;       _Pragma("unroll") for (int kb = 0; kb < 4; ++kb) _Pragma("unroll") for (int j = 0; j < 4; ++j) m_ = fmaxf(m_, S[g][kb][j]); pm[g] = m_; } } while (0)
; DEV void diff16_pass(const bf16_t* __restrict__ proj, int qcol, int kcol, int vcol, int q0, f32x4 (&o)[2][8], f32x4 (&l_out)[2], unsigned char* lds) {
;     ...
;     *reinterpret_cast<bf16x8*>(lds + D_QOFF + wid * 4096 + (g * 2 + 0) * 1024 + lane * 16) = *reinterpret_cast<const bf16x8*>(Qw);
;     *reinterpret_cast<bf16x8*>(lds + D_QOFF + wid * 4096 + (g * 2 + 1) * 1024 + lane * 16) = *reinterpret_cast<const bf16x8*>(Qw + 32); }
;   const int c0 = q0 >> 6, NT = c0 + 4, lim0 = c0 + (fr >> 3), lim1 = c0 + 2 + (fr >> 3);
;   const int kf = ((fr >> 1) & 1) | ((fr >> 2) << 1);
;   const lds_cptr krd = (lds_cptr)shm_raw + D_KOFF + (8 * (fr >> 2) + (fr & 3)) * 128;
;   const int kch0 = ((0 + fq) ^ kf) << 4, kch1 = ((4 + fq) ^ kf) << 4;
;   const int vlane = (fq >> 1) * 512 + (fq & 1) * 256 + (fr >> 2) * 64 + (fr & 3) * 8;
;   const lds_cptr vrdE = (lds_cptr)shm_raw + vlane + (fq & 1) * 32, vrdO = (lds_cptr)shm_raw + vlane + (1 - (fq & 1)) * 32;
;   typedef unsigned char __attribute__((address_space(3))) lds_u8w;
;   lds_u8w* ldsw = (lds_u8w*)shm_raw;
;   unsigned Kg, Vg0, Vg1;
;   { const int r = tid >> 3, fK = ((r >> 1) & 1) | (((r >> 3) & 3) << 1); Kg = (unsigned)(r * INW + kcol + (((tid & 7) ^ fK) * 8)) * 2u;
;     ...
;     VSRC(tid, Vg0); VSRC(512 + tid, Vg1);
;     ...
;   }
;   const unsigned dmaw = (unsigned)__builtin_amdgcn_readfirstlane(wid) * 1024u;
;     ...
;   DMA(0); DMA(1); DMA(2); VWAIT(3); LBAR();
;   { QKT16(SA, 0); float pm_[2]; ROWMAXF16(SA, pm_); RESCALE16(SA, pm_, alA, rfA, true); alA[0] = 1.f; alA[1] = 1.f; rfA = false; EXP16(SA); }
	ds_write_b128 v228, v[0:3]
	ds_write_b128 v228, v[96:99] offset:1024
	ds_write_b128 v228, v[100:103] offset:2048
	ds_write_b128 v228, v[104:107] offset:3072
	v_or_b32_e32 v6, 4, v10
	s_movk_i32 s0, 0x1800
	v_lshrrev_b32_e32 v14, 5, v8
	v_and_b32_e32 v14, 6, v14
	v_bfe_u32 v2, v8, 2, 2
	v_bfe_u32 v1, v8, 1, 1
	v_lshlrev_b32_e32 v3, 1, v2
	v_bitop3_b32 v5, v3, v10, v1 bitop3:0x36
	v_bitop3_b32 v1, v3, v6, v1 bitop3:0x36
	v_bfe_u32 v6, v227, 4, 1
	v_lshlrev_b32_e32 v7, 8, v6
	v_lshlrev_b32_e32 v48, 5, v6
	v_lshrrev_b32_e32 v6, 3, v8
	v_and_b32_e32 v3, 0x200, v11
	v_mul_lo_u32 v6, v6, s0
	v_readlane_b32 s0, v255, 49
	v_add3_u32 v3, 0, v3, v7
	v_lshrrev_b32_e32 v7, 4, v8
	v_bfe_u32 v11, v8, 4, 1
	v_add_lshl_u32 v6, s0, v6, 1
	s_mov_b32 s0, 0x1fffe0
	v_bitop3_b32 v11, v11, v13, v14 bitop3:0x36
	v_bfe_u32 v13, v8, 1, 27
	v_and_or_b32 v16, v7, s0, v15
	v_readlane_b32 s0, v255, 50
	v_xor_b32_e32 v7, v13, v7
	v_lshrrev_b32_e32 v0, 1, v8
	v_and_or_b32 v12, v12, 8, s0
	s_mov_b32 s0, 0xffffe0
	v_and_b32_e32 v14, 24, v13
	v_lshlrev_b32_e32 v7, 4, v7
	v_and_or_b32 v15, v17, s0, v15
	v_lshlrev_b32_e32 v4, 10, v2
	v_lshlrev_b32_e32 v10, 6, v2
	v_or3_b32 v16, v16, v2, v14
	v_and_b32_e32 v0, 0x60, v0
	v_and_b32_e32 v7, 16, v7
	v_or3_b32 v2, v15, v2, v14
	v_and_b32_e32 v13, 0x60, v13
	v_readfirstlane_b32 s0, v9
	v_mul_u32_u24_e32 v16, 0x1800, v16
	v_or3_b32 v0, v0, v7, v12
	v_mul_i32_i24_e32 v2, 0x1800, v2
	v_or3_b32 v7, v13, v7, v12
	v_and_b32_e32 v8, 3, v8
	s_lshl_b32 s0, s0, 10
	v_lshlrev_b32_e32 v231, 4, v1
	v_lshlrev_b32_e32 v1, 3, v8
	v_lshl_or_b32 v232, v11, 4, v6
	v_add_lshl_u32 v233, v0, v16, 1
	v_add_lshl_u32 v234, v7, v2, 1
	s_add_i32 s17, s15, s0
	v_add3_u32 v49, v3, v10, v1
	v_mov_b32_e32 v0, v233
	v_mov_b32_e32 v1, v232
	v_mov_b32_e32 v2, v234
	s_mov_b32 m0, s17
	s_add_i32 s18, s0, 0
	v_readlane_b32 s0, v253, 33
	global_load_lds_dwordx4 v1, s[86:87]
	s_mov_b32 m0, s18
	v_mov_b32_e32 v1, v232
	global_load_lds_dwordx4 v0, s[86:87]
	s_add_i32 m0, s18, 0x2000
	v_mov_b32_e32 v0, v233
	global_load_lds_dwordx4 v2, s[86:87]
	v_mov_b32_e32 v2, v234
	s_add_i32 m0, s18, 0x12000
	v_readlane_b32 s1, v253, 34
	v_lshlrev_b32_e32 v9, 7, v8
	v_add3_u32 v229, s15, v4, v9
	v_lshlrev_b32_e32 v230, 4, v5
	v_add_u32_e32 v50, v229, v230
	s_nop 0
	global_load_lds_dwordx4 v1, s[0:1]
	s_add_i32 m0, s18, 0x4000
	v_mov_b32_e32 v1, v232
	global_load_lds_dwordx4 v0, s[0:1]
	s_add_i32 m0, s18, 0x6000
	v_mov_b32_e32 v0, v233
	global_load_lds_dwordx4 v2, s[0:1]
	v_readlane_b32 s0, v253, 35
	v_mov_b32_e32 v2, v234
	s_add_i32 m0, s18, 0x14000
	v_readlane_b32 s1, v253, 36
	v_add_u32_e32 v51, v229, v231
	v_add_u32_e32 v223, v49, v48
	v_xad_u32 v224, v48, 32, v49
	s_nop 1
	global_load_lds_dwordx4 v1, s[0:1]
	s_add_i32 m0, s18, 0x8000
	s_nop 0
	global_load_lds_dwordx4 v0, s[0:1]
	s_add_i32 m0, s18, 0xa000
	s_cmp_gt_i32 s81, -1
	global_load_lds_dwordx4 v2, s[0:1]
	s_waitcnt vmcnt(3)
	s_waitcnt lgkmcnt(0)
	s_barrier
	ds_read_b128 v[24:27], v228
	ds_read_b128 v[28:31], v228 offset:1024
	ds_read_b128 v[32:35], v228 offset:2048
	ds_read_b128 v[36:39], v228 offset:3072
	ds_read_b128 v[0:3], v50
	ds_read_b128 v[4:7], v51
	s_waitcnt lgkmcnt(0)
	v_mfma_f32_16x16x32_bf16 v[8:11], v[0:3], v[24:27], 0
	s_cselect_b64 s[10:11], -1, 0
	s_cmp_lt_i32 s81, 0
	v_mfma_f32_16x16x32_bf16 v[12:15], v[0:3], v[32:35], 0
	v_mfma_f32_16x16x32_bf16 v[0:3], v[4:7], v[28:31], v[8:11]
	v_mfma_f32_16x16x32_bf16 v[4:7], v[4:7], v[36:39], v[12:15]
	s_nop 2
	ds_read_b128 v[8:11], v50 offset:512
	s_nop 1
	ds_read_b128 v[12:15], v51 offset:512
	s_waitcnt lgkmcnt(0)
	v_mfma_f32_16x16x32_bf16 v[16:19], v[8:11], v[24:27], 0
	v_mfma_f32_16x16x32_bf16 v[20:23], v[8:11], v[32:35], 0
	v_mfma_f32_16x16x32_bf16 v[8:11], v[12:15], v[28:31], v[16:19]
	v_mfma_f32_16x16x32_bf16 v[16:19], v[12:15], v[36:39], v[20:23]
	ds_read_b128 v[12:15], v50 offset:4096
	s_nop 4
	ds_read_b128 v[20:23], v51 offset:4096
	s_waitcnt lgkmcnt(0)
	v_mfma_f32_16x16x32_bf16 v[40:43], v[12:15], v[24:27], 0
	v_mfma_f32_16x16x32_bf16 v[44:47], v[12:15], v[32:35], 0
	v_mfma_f32_16x16x32_bf16 v[12:15], v[20:23], v[28:31], v[40:43]
	v_mfma_f32_16x16x32_bf16 v[20:23], v[20:23], v[36:39], v[44:47]
	s_nop 4
	ds_read_b128 v[40:43], v50 offset:4608
	ds_read_b128 v[44:47], v51 offset:4608
	s_waitcnt lgkmcnt(0)
	v_mfma_f32_16x16x32_bf16 v[24:27], v[40:43], v[24:27], 0
	v_mfma_f32_16x16x32_bf16 v[32:35], v[40:43], v[32:35], 0
	v_mfma_f32_16x16x32_bf16 v[24:27], v[44:47], v[28:31], v[24:27]
	v_mfma_f32_16x16x32_bf16 v[28:31], v[44:47], v[36:39], v[32:35]
	s_nop 5
	v_max_f32_e32 v32, v1, v1
	v_max_f32_e32 v33, v0, v0
	v_max_f32_e32 v32, v33, v32
	v_max_f32_e32 v33, v5, v5
	v_max_f32_e32 v34, v4, v4
	v_max_f32_e32 v33, v34, v33
	v_max3_f32 v32, v32, v2, v3
	v_max3_f32 v33, v33, v6, v7
	v_max3_f32 v32, v32, v8, v9
	v_max3_f32 v33, v33, v16, v17
	v_max3_f32 v32, v32, v10, v11
	v_max3_f32 v33, v33, v18, v19
	v_max3_f32 v32, v32, v12, v13
	v_max3_f32 v33, v33, v20, v21
	v_max3_f32 v32, v32, v14, v15
	v_max3_f32 v33, v33, v22, v23
	v_max3_f32 v32, v32, v24, v25
	v_max3_f32 v33, v33, v28, v29
	v_max3_f32 v32, v32, v26, v27
	v_max3_f32 v34, v33, v30, v31
	ds_bpermute_b32 v33, v217, v32
	ds_bpermute_b32 v35, v217, v34
	s_waitcnt lgkmcnt(0)
	v_max_f32_e32 v33, v33, v33
	v_max_f32_e32 v35, v35, v35
	v_max_f32_e32 v32, v32, v33
	v_max_f32_e32 v34, v34, v35
	ds_bpermute_b32 v33, v216, v32
	ds_bpermute_b32 v35, v216, v34
	s_cbranch_scc1 .LBB0_391
; #define VWAIT(n) asm volatile("s_waitcnt vmcnt(" #n ")" ::: "memory")
; #define LBAR() do { asm volatile("s_waitcnt lgkmcnt(0)" ::: "memory"); __builtin_amdgcn_s_barrier(); } while (0)
; #define VWAIT(n) asm volatile("s_waitcnt vmcnt(" #n ")" ::: "memory")
; #define LBAR() do { asm volatile("s_waitcnt lgkmcnt(0)" ::: "memory"); __builtin_amdgcn_s_barrier(); } while (0)
; #define ROWMAXF16(S, pm) do { _Pragma("unroll") for (int g = 0; g < 2; ++g) { float m_ = S[g][0][0]; \
;       _Pragma("unroll") for (int kb = 0; kb < 4; ++kb) _Pragma("unroll") for (int j = 0; j < 4; ++j) m_ = fmaxf(m_, S[g][kb][j]); pm[g] = m_; } } while (0)
; #define EXP16(S) do { _Pragma("unroll") for (int g = 0; g < 2; ++g) _Pragma("unroll") for (int kb = 0; kb < 4; ++kb) _Pragma("unroll") for (int j = 0; j < 4; ++j) S[g][kb][j] = __builtin_amdgcn_exp2f(S[g][kb][j]); } while (0)
; DEV void diff16_pass(const bf16_t* __restrict__ proj, int qcol, int kcol, int vcol, int q0, f32x4 (&o)[2][8], f32x4 (&l_out)[2], unsigned char* lds) {
;     ...
;   float m_reg[2] = {0.f, 0.f};
;   f32x4 ol[2] = {(f32x4){0.f, 0.f, 0.f, 0.f}, (f32x4){0.f, 0.f, 0.f, 0.f}};
;   const bf16x8 ones = {0x3F80, 0x3F80, 0x3F80, 0x3F80, 0x3F80, 0x3F80, 0x3F80, 0x3F80};
;   f32x4 negm[2] = {(f32x4){0.f, 0.f, 0.f, 0.f}, (f32x4){0.f, 0.f, 0.f, 0.f}};
; #pragma unroll
;   for (int g = 0; g < 2; ++g)
; #pragma unroll
;     for (int cb = 0; cb < 8; ++cb) o[g][cb] = (f32x4){0.f, 0.f, 0.f, 0.f};
;   f32x4 SA[2][4], SB2[2][4]; float alA[2], alB[2]; bool rfA = false, rfB = false; bf16x8 pa[2][2];
;   DMA(0); DMA(1); DMA(2); VWAIT(3); LBAR();
;   { QKT16(SA, 0); float pm_[2]; ROWMAXF16(SA, pm_); RESCALE16(SA, pm_, alA, rfA, true); alA[0] = 1.f; alA[1] = 1.f; rfA = false; EXP16(SA); }
	s_waitcnt lgkmcnt(0)
	v_max_f32_e32 v35, v35, v35
	v_max_f32_e32 v34, v34, v34
	v_max_f32_e32 v35, v34, v35
	v_sub_f32_e32 v5, v5, v35
	v_sub_f32_e32 v4, v4, v35
	v_exp_f32_e32 v137, v4
	v_exp_f32_e32 v148, v5
	v_max_f32_e32 v4, v33, v33
	v_max_f32_e32 v5, v32, v32
	v_sub_f32_e32 v7, v7, v35
	v_sub_f32_e32 v6, v6, v35
	v_max_f32_e32 v34, v5, v4
	v_exp_f32_e32 v149, v6
	v_exp_f32_e32 v151, v7
	v_sub_f32_e32 v4, v27, v34
	v_sub_f32_e32 v5, v26, v34
	v_sub_f32_e32 v6, v25, v34
	v_sub_f32_e32 v7, v24, v34
	v_exp_f32_e32 v152, v7
	v_exp_f32_e32 v154, v6
	v_exp_f32_e32 v155, v5
	v_exp_f32_e32 v157, v4
	v_sub_f32_e32 v4, v15, v34
	v_sub_f32_e32 v5, v14, v34
	v_sub_f32_e32 v6, v13, v34
	v_sub_f32_e32 v7, v12, v34
	v_sub_f32_e32 v31, v31, v35
	v_sub_f32_e32 v30, v30, v35
	v_sub_f32_e32 v29, v29, v35
	v_sub_f32_e32 v28, v28, v35
	v_sub_f32_e32 v23, v23, v35
	v_sub_f32_e32 v22, v22, v35
	v_sub_f32_e32 v21, v21, v35
	v_sub_f32_e32 v20, v20, v35
	v_sub_f32_e32 v19, v19, v35
	v_sub_f32_e32 v18, v18, v35
	v_sub_f32_e32 v17, v17, v35
	v_sub_f32_e32 v16, v16, v35
	v_exp_f32_e32 v153, v7
	v_exp_f32_e32 v156, v6
	v_exp_f32_e32 v158, v5
	v_exp_f32_e32 v159, v4
	v_sub_f32_e32 v4, v11, v34
	v_sub_f32_e32 v5, v10, v34
	v_sub_f32_e32 v6, v9, v34
	v_sub_f32_e32 v7, v8, v34
	v_sub_f32_e32 v3, v3, v34
	v_sub_f32_e32 v2, v2, v34
	v_sub_f32_e32 v1, v1, v34
	v_sub_f32_e32 v0, v0, v34
	v_exp_f32_e32 v128, v28
	v_exp_f32_e32 v130, v29
	v_exp_f32_e32 v131, v30
	v_exp_f32_e32 v133, v31
	v_exp_f32_e32 v129, v20
	v_exp_f32_e32 v134, v21
	v_exp_f32_e32 v135, v22
	v_exp_f32_e32 v138, v23
	v_exp_f32_e32 v132, v16
	v_exp_f32_e32 v136, v17
	v_exp_f32_e32 v139, v18
	v_exp_f32_e32 v150, v19
	v_exp_f32_e32 v240, v7
	v_exp_f32_e32 v242, v6
	v_exp_f32_e32 v243, v5
	v_exp_f32_e32 v246, v4
	v_exp_f32_e32 v241, v0
	v_exp_f32_e32 v244, v1
	v_exp_f32_e32 v245, v2
	v_exp_f32_e32 v247, v3
	v_lshrrev_b32_e32 v36, 3, v226
	v_pk_add_f32 v[208:209], v[34:35], 0 op_sel_hi:[1,0]
	v_mov_b32_e32 v2, v193
	v_mov_b32_e32 v3, v193
	v_or_b32_e32 v235, s75, v36
	v_xor_b32_e32 v76, 0x80000000, v209
	v_pk_add_f32 v[72:73], v[208:209], 0 neg_lo:[1,1] neg_hi:[1,1]
	v_mov_b32_e32 v0, v193
	v_mov_b32_e32 v1, v193
	v_mov_b64_e32 v[10:11], v[2:3]
	v_mov_b64_e32 v[26:27], v[2:3]
	v_mov_b64_e32 v[18:19], v[2:3]
	v_mov_b64_e32 v[38:39], v[2:3]
	v_mov_b64_e32 v[42:43], v[2:3]
	v_mov_b64_e32 v[50:51], v[2:3]
	v_mov_b64_e32 v[66:67], v[2:3]
	v_mov_b64_e32 v[6:7], v[2:3]
	v_mov_b64_e32 v[14:15], v[2:3]
	v_mov_b64_e32 v[30:31], v[2:3]
	v_mov_b64_e32 v[22:23], v[2:3]
	v_mov_b64_e32 v[34:35], v[2:3]
	v_mov_b64_e32 v[46:47], v[2:3]
	v_mov_b64_e32 v[54:55], v[2:3]
	v_mov_b64_e32 v[62:63], v[2:3]
	v_mov_b64_e32 v[70:71], v[2:3]
	v_mov_b64_e32 v[58:59], v[2:3]
	v_or_b32_e32 v236, 2, v235
	v_cmp_gt_u32_e64 s[4:5], 16, v227
	v_lshl_add_u32 v237, v226, 2, v225
	s_mov_b32 s23, 1
	s_mov_b64 s[6:7], 0
	v_mov_b32_e32 v249, 1.0
	s_mov_b32 s19, 0x10000
	s_movk_i32 s20, 0x4000
	v_mov_b64_e32 v[8:9], v[0:1]
	v_mov_b64_e32 v[24:25], v[0:1]
	v_mov_b64_e32 v[16:17], v[0:1]
	v_mov_b64_e32 v[36:37], v[0:1]
	v_mov_b64_e32 v[40:41], v[0:1]
	v_mov_b64_e32 v[48:49], v[0:1]
	v_mov_b64_e32 v[64:65], v[0:1]
	v_mov_b64_e32 v[4:5], v[0:1]
	v_mov_b64_e32 v[12:13], v[0:1]
	v_mov_b64_e32 v[28:29], v[0:1]
	v_mov_b64_e32 v[20:21], v[0:1]
	v_mov_b64_e32 v[32:33], v[0:1]
	v_mov_b64_e32 v[44:45], v[0:1]
	v_mov_b64_e32 v[52:53], v[0:1]
	v_mov_b64_e32 v[60:61], v[0:1]
	v_mov_b32_e32 v248, 1.0
	v_mov_b64_e32 v[68:69], v[0:1]
	v_mov_b64_e32 v[56:57], v[0:1]
	v_mov_b32_e32 v73, v72
	v_mov_b32_e32 v74, v72
	v_mov_b32_e32 v75, v72
	v_mov_b32_e32 v77, v76
	v_mov_b32_e32 v78, v76
	v_mov_b32_e32 v79, v76
	s_cmp_lt_u32 s18, 0x1000
	s_cbranch_scc1 .Lprio_a
	s_setprio 1
